# 8 MFMAs of each 32-MFMA block issued ahead of the K-loop barrier (was 4)
# speedup vs baseline: 1.0089x; 1.0089x over previous
; #define PG8_STAGE(bufoff, gbase, voff) do { _Pragma("unroll") for (int _i = 0; _i < 2; ++_i) \
;         __builtin_amdgcn_global_load_lds((const unsigned*)((const char*)(gbase) + (voff)[_i]), (PG8_LAS unsigned*)(lds + (bufoff) + ldsw + _i * 8192), 16, 0, 0); } while (0)
; #define PG8_LDA(dst, b, h) do { _Pragma("unroll") for (int m = 0; m < 4; ++m) _Pragma("unroll") for (int k = 0; k < 2; ++k) dst[m][k] = *(const PG8_LAS bf16x8*)(lds + PG8_SA(b, h) + aoff + m * 2048 + k * 1024); } while (0)
; #define PG8_LDB(dst, b, h) do { _Pragma("unroll") for (int n = 0; n < 2; ++n) _Pragma("unroll") for (int k = 0; k < 2; ++k) dst[n][k] = *(const PG8_LAS bf16x8*)(lds + PG8_SB(b, h) + boff + n * 2048 + k * 1024); } while (0)
; #define PG8_MMA(ai, bj, At, Bt) do { __builtin_amdgcn_s_setprio(1); _Pragma("unroll") for (int m = 0; m < 4; ++m) _Pragma("unroll") for (int n = 0; n < 2; ++n) _Pragma("unroll") for (int k = 0; k < 2; ++k) \
;         acc[ai][bj][m][n] = __builtin_amdgcn_mfma_f32_16x16x32_bf16(Bt[n][k], At[m][k], acc[ai][bj][m][n], 0, 0, 0); __builtin_amdgcn_s_setprio(0); } while (0)
; #define PG8_WAIT_V(n) asm volatile("s_waitcnt vmcnt(" #n ")" ::: "memory")
; #define PG8_WAIT_L(n) asm volatile("s_waitcnt lgkmcnt(" #n ")" ::: "memory")
; #define PG8_BAR __builtin_amdgcn_s_barrier()
; #define PG8_SCHED __builtin_amdgcn_sched_barrier(0)
; template <class Epi, class Sched, bool ALIGN_EPI = false, bool SP2 = false>
; __device__ __forceinline__ void gemm_phase(PG8_LAS unsigned char* lds, const Gemm g, const Sched& S, const Epi& E) {
;     ...
;             if constexpr (SP2) {
;             PG8_LDB(B0, 0, 0); PG8_LDB(B1, 0, 1); PG8_SCHED; PG8_LDA(At, 0, 0); PG8_STAGE(PG8_SA(1, 1), a1 + hstep, voffA);
;             PG8_WAIT_V(8); PG8_WAIT_L(0); PG8_BAR; PG8_MMA(0, 0, At, B0); PG8_MMA(0, 1, At, B1); PG8_BAR; PG8_SCHED;
;             PG8_LDA(At, 0, 1); PG8_STAGE(PG8_SB(0, 0), b2, voffB); PG8_STAGE(PG8_SB(0, 1), b2 + hstep, voffB); PG8_STAGE(PG8_SA(0, 0), a2, voffA);
;             PG8_WAIT_V(8); PG8_WAIT_L(0); PG8_BAR; PG8_MMA(1, 0, At, B0); PG8_MMA(1, 1, At, B1); PG8_BAR; PG8_SCHED;
.LBB0_49:
	s_add_u32 s40, s0, 0xfffe0080
	s_addc_u32 s41, s1, -1
	s_add_i32 s65, 0, 0x10000
	s_cmp_eq_u32 s64, 4
	s_cselect_b32 s43, s19, s41
	s_cselect_b32 s42, s60, s40
	s_cselect_b32 s41, s17, s63
	s_cselect_b32 s40, s61, s62
	s_add_i32 s68, 0, 0x14000
	v_add_u32_e32 v144, s65, v248
	v_add_u32_e32 v160, s68, v248
	ds_read_b128 v[132:135], v144
	ds_read_b128 v[136:139], v144 offset:1024
	ds_read_b128 v[140:143], v144 offset:2048
	ds_read_b128 v[144:147], v144 offset:3072
	ds_read_b128 v[148:151], v160
	ds_read_b128 v[152:155], v160 offset:1024
	ds_read_b128 v[156:159], v160 offset:2048
	ds_read_b128 v[160:163], v160 offset:3072
	v_lshl_add_u64 v[210:211], s[0:1], 0, v[206:207]
	s_add_i32 m0, s51, 0xc000
	ds_read_b128 v[164:167], v250
	ds_read_b128 v[168:171], v250 offset:1024
	ds_read_b128 v[172:175], v250 offset:2048
	ds_read_b128 v[176:179], v250 offset:3072
	ds_read_b128 v[180:183], v250 offset:4096
	ds_read_b128 v[184:187], v250 offset:5120
	ds_read_b128 v[188:191], v250 offset:6144
	ds_read_b128 v[192:195], v250 offset:7168
	global_load_lds_dwordx4 v[210:211], off
	v_lshl_add_u64 v[210:211], s[0:1], 0, v[208:209]
	s_add_i32 m0, s51, 0xe000
	s_nop 0
	global_load_lds_dwordx4 v[210:211], off
	s_waitcnt vmcnt(8)
	s_waitcnt lgkmcnt(0)
	v_mfma_f32_16x16x32_bf16 v[128:131], v[132:135], v[164:167], v[128:131]
	v_mfma_f32_16x16x32_bf16 v[124:127], v[140:143], v[164:167], v[124:127]
	v_mfma_f32_16x16x32_bf16 v[116:119], v[132:135], v[172:175], v[116:119]
	v_mfma_f32_16x16x32_bf16 v[108:111], v[140:143], v[172:175], v[108:111]
	v_mfma_f32_16x16x32_bf16 v[100:103], v[132:135], v[180:183], v[100:103]
	v_mfma_f32_16x16x32_bf16 v[92:95], v[140:143], v[180:183], v[92:95]
	v_mfma_f32_16x16x32_bf16 v[84:87], v[132:135], v[188:191], v[84:87]
	v_mfma_f32_16x16x32_bf16 v[76:79], v[140:143], v[188:191], v[76:79]
	s_barrier
	s_setprio 1
	v_mfma_f32_16x16x32_bf16 v[128:131], v[136:139], v[168:171], v[128:131]
	v_mfma_f32_16x16x32_bf16 v[124:127], v[144:147], v[168:171], v[124:127]
	v_mfma_f32_16x16x32_bf16 v[116:119], v[136:139], v[176:179], v[116:119]
	v_mfma_f32_16x16x32_bf16 v[108:111], v[144:147], v[176:179], v[108:111]
	v_mfma_f32_16x16x32_bf16 v[100:103], v[136:139], v[184:187], v[100:103]
	v_mfma_f32_16x16x32_bf16 v[92:95], v[144:147], v[184:187], v[92:95]
	v_mfma_f32_16x16x32_bf16 v[84:87], v[136:139], v[192:195], v[84:87]
	v_mfma_f32_16x16x32_bf16 v[76:79], v[144:147], v[192:195], v[76:79]
	s_setprio 0
	s_setprio 1
	v_mfma_f32_16x16x32_bf16 v[120:123], v[148:151], v[164:167], v[120:123]
	v_mfma_f32_16x16x32_bf16 v[112:115], v[156:159], v[164:167], v[112:115]
	v_mfma_f32_16x16x32_bf16 v[104:107], v[148:151], v[172:175], v[104:107]
	v_mfma_f32_16x16x32_bf16 v[96:99], v[156:159], v[172:175], v[96:99]
	v_mfma_f32_16x16x32_bf16 v[88:91], v[148:151], v[180:183], v[88:91]
	v_mfma_f32_16x16x32_bf16 v[80:83], v[156:159], v[180:183], v[80:83]
	v_mfma_f32_16x16x32_bf16 v[72:75], v[148:151], v[188:191], v[72:75]
	v_mfma_f32_16x16x32_bf16 v[68:71], v[156:159], v[188:191], v[68:71]
	v_mfma_f32_16x16x32_bf16 v[120:123], v[152:155], v[168:171], v[120:123]
	v_mfma_f32_16x16x32_bf16 v[112:115], v[160:163], v[168:171], v[112:115]
	v_mfma_f32_16x16x32_bf16 v[104:107], v[152:155], v[176:179], v[104:107]
	v_mfma_f32_16x16x32_bf16 v[96:99], v[160:163], v[176:179], v[96:99]
	v_mfma_f32_16x16x32_bf16 v[88:91], v[152:155], v[184:187], v[88:91]
	v_mfma_f32_16x16x32_bf16 v[80:83], v[160:163], v[184:187], v[80:83]
	v_mfma_f32_16x16x32_bf16 v[72:75], v[152:155], v[192:195], v[72:75]
	v_mfma_f32_16x16x32_bf16 v[68:71], v[160:163], v[192:195], v[68:71]
	s_setprio 0
	s_barrier
	s_add_i32 s65, s65, s50
	v_lshl_add_u64 v[210:211], s[40:41], 0, v[196:197]
	s_mov_b32 m0, s65
	ds_read_b128 v[164:167], v250 offset:16384
	ds_read_b128 v[168:171], v250 offset:17408
	ds_read_b128 v[172:175], v250 offset:18432
	ds_read_b128 v[176:179], v250 offset:19456
	ds_read_b128 v[180:183], v250 offset:20480
	ds_read_b128 v[184:187], v250 offset:21504
	ds_read_b128 v[188:191], v250 offset:22528
	ds_read_b128 v[192:195], v250 offset:23552
	global_load_lds_dwordx4 v[210:211], off
	s_add_i32 m0, s65, 0x2000
	s_add_u32 s66, s40, 0x20000
	v_lshl_add_u64 v[212:213], s[40:41], 0, v[32:33]
	s_addc_u32 s67, s41, 0
	s_add_i32 s65, s68, s50
	global_load_lds_dwordx4 v[212:213], off
	v_lshl_add_u64 v[214:215], s[66:67], 0, v[196:197]
	s_mov_b32 m0, s65
	v_lshl_add_u64 v[216:217], s[42:43], 0, v[202:203]
	global_load_lds_dwordx4 v[214:215], off
	v_lshl_add_u64 v[214:215], s[66:67], 0, v[32:33]
	s_add_i32 m0, s65, 0x2000
	s_nop 0
	global_load_lds_dwordx4 v[214:215], off
	v_lshl_add_u64 v[214:215], s[42:43], 0, v[204:205]
	s_mov_b32 m0, s51
	s_nop 0
	global_load_lds_dwordx4 v[214:215], off
	s_mov_b32 m0, s52
	s_nop 0
	global_load_lds_dwordx4 v[216:217], off
	s_waitcnt vmcnt(8)
	s_waitcnt lgkmcnt(0)
	v_mfma_f32_16x16x32_bf16 v[64:67], v[132:135], v[164:167], v[64:67]
	v_mfma_f32_16x16x32_bf16 v[60:63], v[140:143], v[164:167], v[60:63]
	v_mfma_f32_16x16x32_bf16 v[52:55], v[132:135], v[172:175], v[52:55]
	v_mfma_f32_16x16x32_bf16 v[44:47], v[140:143], v[172:175], v[44:47]
	v_mfma_f32_16x16x32_bf16 v[36:39], v[132:135], v[180:183], v[36:39]
	v_mfma_f32_16x16x32_bf16 v[24:27], v[140:143], v[180:183], v[24:27]
	v_mfma_f32_16x16x32_bf16 v[16:19], v[132:135], v[188:191], v[16:19]
	v_mfma_f32_16x16x32_bf16 v[8:11], v[140:143], v[188:191], v[8:11]
	s_barrier
; #define PG8_STAGE(bufoff, gbase, voff) do { _Pragma("unroll") for (int _i = 0; _i < 2; ++_i) \
;         __builtin_amdgcn_global_load_lds((const unsigned*)((const char*)(gbase) + (voff)[_i]), (PG8_LAS unsigned*)(lds + (bufoff) + ldsw + _i * 8192), 16, 0, 0); } while (0)
; #define PG8_LDA(dst, b, h) do { _Pragma("unroll") for (int m = 0; m < 4; ++m) _Pragma("unroll") for (int k = 0; k < 2; ++k) dst[m][k] = *(const PG8_LAS bf16x8*)(lds + PG8_SA(b, h) + aoff + m * 2048 + k * 1024); } while (0)
; #define PG8_LDB(dst, b, h) do { _Pragma("unroll") for (int n = 0; n < 2; ++n) _Pragma("unroll") for (int k = 0; k < 2; ++k) dst[n][k] = *(const PG8_LAS bf16x8*)(lds + PG8_SB(b, h) + boff + n * 2048 + k * 1024); } while (0)
; #define PG8_MMA(ai, bj, At, Bt) do { __builtin_amdgcn_s_setprio(1); _Pragma("unroll") for (int m = 0; m < 4; ++m) _Pragma("unroll") for (int n = 0; n < 2; ++n) _Pragma("unroll") for (int k = 0; k < 2; ++k) \
;         acc[ai][bj][m][n] = __builtin_amdgcn_mfma_f32_16x16x32_bf16(Bt[n][k], At[m][k], acc[ai][bj][m][n], 0, 0, 0); __builtin_amdgcn_s_setprio(0); } while (0)
; #define PG8_WAIT_V(n) asm volatile("s_waitcnt vmcnt(" #n ")" ::: "memory")
; #define PG8_WAIT_L(n) asm volatile("s_waitcnt lgkmcnt(" #n ")" ::: "memory")
; #define PG8_BAR __builtin_amdgcn_s_barrier()
; #define PG8_SCHED __builtin_amdgcn_sched_barrier(0)
; template <class Epi, class Sched, bool ALIGN_EPI = false, bool SP2 = false>
; __device__ __forceinline__ void gemm_phase(PG8_LAS unsigned char* lds, const Gemm g, const Sched& S, const Epi& E) {
;     ...
;             PG8_WAIT_V(8); PG8_WAIT_L(0); PG8_BAR; PG8_MMA(1, 0, At, B0); PG8_MMA(1, 1, At, B1); PG8_BAR; PG8_SCHED;
;             PG8_LDB(B0, 1, 0); PG8_LDB(B1, 1, 1); PG8_SCHED; PG8_LDA(At, 1, 0); PG8_STAGE(PG8_SA(0, 1), a2 + hstep, voffA);
;             PG8_WAIT_V(8); PG8_WAIT_L(0); PG8_BAR; PG8_MMA(0, 0, At, B0); PG8_MMA(0, 1, At, B1); PG8_BAR; PG8_SCHED;
	s_setprio 1
	v_mfma_f32_16x16x32_bf16 v[64:67], v[136:139], v[168:171], v[64:67]
	v_mfma_f32_16x16x32_bf16 v[60:63], v[144:147], v[168:171], v[60:63]
	v_mfma_f32_16x16x32_bf16 v[52:55], v[136:139], v[176:179], v[52:55]
	v_mfma_f32_16x16x32_bf16 v[44:47], v[144:147], v[176:179], v[44:47]
	v_mfma_f32_16x16x32_bf16 v[36:39], v[136:139], v[184:187], v[36:39]
	v_mfma_f32_16x16x32_bf16 v[24:27], v[144:147], v[184:187], v[24:27]
	v_mfma_f32_16x16x32_bf16 v[16:19], v[136:139], v[192:195], v[16:19]
	v_mfma_f32_16x16x32_bf16 v[8:11], v[144:147], v[192:195], v[8:11]
	s_setprio 0
	s_setprio 1
	v_mfma_f32_16x16x32_bf16 v[56:59], v[148:151], v[164:167], v[56:59]
	v_mfma_f32_16x16x32_bf16 v[48:51], v[156:159], v[164:167], v[48:51]
	v_mfma_f32_16x16x32_bf16 v[40:43], v[148:151], v[172:175], v[40:43]
	v_mfma_f32_16x16x32_bf16 v[28:31], v[156:159], v[172:175], v[28:31]
	v_mfma_f32_16x16x32_bf16 v[20:23], v[148:151], v[180:183], v[20:23]
	v_mfma_f32_16x16x32_bf16 v[12:15], v[156:159], v[180:183], v[12:15]
	v_mfma_f32_16x16x32_bf16 v[4:7], v[148:151], v[188:191], v[4:7]
	v_mfma_f32_16x16x32_bf16 v[0:3], v[156:159], v[188:191], v[0:3]
	v_mfma_f32_16x16x32_bf16 v[56:59], v[152:155], v[168:171], v[56:59]
	v_mfma_f32_16x16x32_bf16 v[48:51], v[160:163], v[168:171], v[48:51]
	v_mfma_f32_16x16x32_bf16 v[40:43], v[152:155], v[176:179], v[40:43]
	v_mfma_f32_16x16x32_bf16 v[28:31], v[160:163], v[176:179], v[28:31]
	v_mfma_f32_16x16x32_bf16 v[20:23], v[152:155], v[184:187], v[20:23]
	v_mfma_f32_16x16x32_bf16 v[12:15], v[160:163], v[184:187], v[12:15]
	v_mfma_f32_16x16x32_bf16 v[4:7], v[152:155], v[192:195], v[4:7]
	v_mfma_f32_16x16x32_bf16 v[0:3], v[160:163], v[192:195], v[0:3]
	s_setprio 0
	s_barrier
	s_add_i32 s65, 0, 0x18000
	s_add_i32 s66, 0, 0x1c000
	v_add_u32_e32 v144, s65, v248
	v_add_u32_e32 v160, s66, v248
	ds_read_b128 v[132:135], v144
	ds_read_b128 v[136:139], v144 offset:1024
	ds_read_b128 v[140:143], v144 offset:2048
	ds_read_b128 v[144:147], v144 offset:3072
	ds_read_b128 v[148:151], v160
	ds_read_b128 v[152:155], v160 offset:1024
	ds_read_b128 v[156:159], v160 offset:2048
	ds_read_b128 v[160:163], v160 offset:3072
	s_add_u32 s42, s42, 0x20000
	s_addc_u32 s43, s43, 0
	s_mov_b32 m0, s53
	v_lshl_add_u64 v[218:219], s[42:43], 0, v[204:205]
	ds_read_b128 v[164:167], v250 offset:32768
	ds_read_b128 v[168:171], v250 offset:33792
	ds_read_b128 v[172:175], v250 offset:34816
	ds_read_b128 v[176:179], v250 offset:35840
	ds_read_b128 v[180:183], v250 offset:36864
	ds_read_b128 v[184:187], v250 offset:37888
	ds_read_b128 v[188:191], v250 offset:38912
	ds_read_b128 v[192:195], v250 offset:39936
	global_load_lds_dwordx4 v[218:219], off
	v_lshl_add_u64 v[218:219], s[42:43], 0, v[202:203]
	s_mov_b32 m0, s54
	s_nop 0
	global_load_lds_dwordx4 v[218:219], off
	s_waitcnt vmcnt(8)
	s_waitcnt lgkmcnt(0)
	v_mfma_f32_16x16x32_bf16 v[128:131], v[132:135], v[164:167], v[128:131]
	v_mfma_f32_16x16x32_bf16 v[124:127], v[140:143], v[164:167], v[124:127]
	v_mfma_f32_16x16x32_bf16 v[116:119], v[132:135], v[172:175], v[116:119]
	v_mfma_f32_16x16x32_bf16 v[108:111], v[140:143], v[172:175], v[108:111]
	v_mfma_f32_16x16x32_bf16 v[100:103], v[132:135], v[180:183], v[100:103]
	v_mfma_f32_16x16x32_bf16 v[92:95], v[140:143], v[180:183], v[92:95]
	v_mfma_f32_16x16x32_bf16 v[84:87], v[132:135], v[188:191], v[84:87]
	v_mfma_f32_16x16x32_bf16 v[76:79], v[140:143], v[188:191], v[76:79]
	s_barrier
	s_setprio 1
	v_mfma_f32_16x16x32_bf16 v[128:131], v[136:139], v[168:171], v[128:131]
	v_mfma_f32_16x16x32_bf16 v[124:127], v[144:147], v[168:171], v[124:127]
	v_mfma_f32_16x16x32_bf16 v[116:119], v[136:139], v[176:179], v[116:119]
	v_mfma_f32_16x16x32_bf16 v[108:111], v[144:147], v[176:179], v[108:111]
	v_mfma_f32_16x16x32_bf16 v[100:103], v[136:139], v[184:187], v[100:103]
	v_mfma_f32_16x16x32_bf16 v[92:95], v[144:147], v[184:187], v[92:95]
	v_mfma_f32_16x16x32_bf16 v[84:87], v[136:139], v[192:195], v[84:87]
	v_mfma_f32_16x16x32_bf16 v[76:79], v[144:147], v[192:195], v[76:79]
	s_setprio 0
	s_setprio 1
	v_mfma_f32_16x16x32_bf16 v[120:123], v[148:151], v[164:167], v[120:123]
	v_mfma_f32_16x16x32_bf16 v[112:115], v[156:159], v[164:167], v[112:115]
	v_mfma_f32_16x16x32_bf16 v[104:107], v[148:151], v[172:175], v[104:107]
	v_mfma_f32_16x16x32_bf16 v[96:99], v[156:159], v[172:175], v[96:99]
	v_mfma_f32_16x16x32_bf16 v[88:91], v[148:151], v[180:183], v[88:91]
	v_mfma_f32_16x16x32_bf16 v[80:83], v[156:159], v[180:183], v[80:83]
	v_mfma_f32_16x16x32_bf16 v[72:75], v[148:151], v[188:191], v[72:75]
	v_mfma_f32_16x16x32_bf16 v[68:71], v[156:159], v[188:191], v[68:71]
	v_mfma_f32_16x16x32_bf16 v[120:123], v[152:155], v[168:171], v[120:123]
	v_mfma_f32_16x16x32_bf16 v[112:115], v[160:163], v[168:171], v[112:115]
	v_mfma_f32_16x16x32_bf16 v[104:107], v[152:155], v[176:179], v[104:107]
	v_mfma_f32_16x16x32_bf16 v[96:99], v[160:163], v[176:179], v[96:99]
	v_mfma_f32_16x16x32_bf16 v[88:91], v[152:155], v[184:187], v[88:91]
	v_mfma_f32_16x16x32_bf16 v[80:83], v[160:163], v[184:187], v[80:83]
	v_mfma_f32_16x16x32_bf16 v[72:75], v[152:155], v[192:195], v[72:75]
	v_mfma_f32_16x16x32_bf16 v[68:71], v[160:163], v[192:195], v[68:71]
	s_setprio 0
	s_barrier
; #define PG8_STAGE(bufoff, gbase, voff) do { _Pragma("unroll") for (int _i = 0; _i < 2; ++_i) \
;         __builtin_amdgcn_global_load_lds((const unsigned*)((const char*)(gbase) + (voff)[_i]), (PG8_LAS unsigned*)(lds + (bufoff) + ldsw + _i * 8192), 16, 0, 0); } while (0)
; #define PG8_LDA(dst, b, h) do { _Pragma("unroll") for (int m = 0; m < 4; ++m) _Pragma("unroll") for (int k = 0; k < 2; ++k) dst[m][k] = *(const PG8_LAS bf16x8*)(lds + PG8_SA(b, h) + aoff + m * 2048 + k * 1024); } while (0)
; #define PG8_MMA(ai, bj, At, Bt) do { __builtin_amdgcn_s_setprio(1); _Pragma("unroll") for (int m = 0; m < 4; ++m) _Pragma("unroll") for (int n = 0; n < 2; ++n) _Pragma("unroll") for (int k = 0; k < 2; ++k) \
;         acc[ai][bj][m][n] = __builtin_amdgcn_mfma_f32_16x16x32_bf16(Bt[n][k], At[m][k], acc[ai][bj][m][n], 0, 0, 0); __builtin_amdgcn_s_setprio(0); } while (0)
; #define PG8_WAIT_V(n) asm volatile("s_waitcnt vmcnt(" #n ")" ::: "memory")
; #define PG8_WAIT_L(n) asm volatile("s_waitcnt lgkmcnt(" #n ")" ::: "memory")
; #define PG8_BAR __builtin_amdgcn_s_barrier()
; #define PG8_SCHED __builtin_amdgcn_sched_barrier(0)
; template <class Epi, class Sched, bool ALIGN_EPI = false, bool SP2 = false>
; __device__ __forceinline__ void gemm_phase(PG8_LAS unsigned char* lds, const Gemm g, const Sched& S, const Epi& E) {
;     ...
;         for (int t = 0; t < nt; t += 2) {
;             const bool last = (t == nt - 2);
;             const char* a1 = cA + (size_t)(t + 1) * kstep;
;             const char* a2 = last ? nA : cA + (size_t)(t + 2) * kstep; const char* b2 = last ? nB : cB + (size_t)(t + 2) * kstep;
;     ...
;             PG8_LDA(At, 1, 1); PG8_STAGE(PG8_SB(1, 0), b3, voffB); PG8_STAGE(PG8_SB(1, 1), b3 + hstep, voffB); PG8_STAGE(PG8_SA(1, 0), a3, voffA);
;             PG8_WAIT_V(8); PG8_WAIT_L(0); PG8_BAR; PG8_MMA(1, 0, At, B0); PG8_MMA(1, 1, At, B1); PG8_BAR; PG8_SCHED;
	s_add_i32 s42, s65, s50
	v_lshl_add_u64 v[210:211], v[210:211], 0, s[36:37]
	s_mov_b32 m0, s42
	ds_read_b128 v[164:167], v250 offset:49152
	ds_read_b128 v[168:171], v250 offset:50176
	ds_read_b128 v[172:175], v250 offset:51200
	ds_read_b128 v[176:179], v250 offset:52224
	ds_read_b128 v[180:183], v250 offset:53248
	ds_read_b128 v[184:187], v250 offset:54272
	ds_read_b128 v[188:191], v250 offset:55296
	ds_read_b128 v[192:195], v250 offset:56320
	global_load_lds_dwordx4 v[210:211], off
	s_add_i32 m0, s42, 0x2000
	s_add_u32 s40, s40, 0x20080
	v_lshl_add_u64 v[210:211], v[212:213], 0, s[36:37]
	s_addc_u32 s41, s41, 0
	s_add_i32 s42, s66, s50
	global_load_lds_dwordx4 v[210:211], off
	v_lshl_add_u64 v[210:211], s[40:41], 0, v[196:197]
	s_mov_b32 m0, s42
	s_nop 0
	global_load_lds_dwordx4 v[210:211], off
	v_lshl_add_u64 v[210:211], s[40:41], 0, v[32:33]
	s_add_i32 m0, s42, 0x2000
	s_nop 0
	global_load_lds_dwordx4 v[210:211], off
	v_lshl_add_u64 v[210:211], v[214:215], 0, s[36:37]
	s_mov_b32 m0, s56
	s_nop 0
	global_load_lds_dwordx4 v[210:211], off
	v_lshl_add_u64 v[210:211], v[216:217], 0, s[36:37]
	s_mov_b32 m0, s57
	s_nop 0
	global_load_lds_dwordx4 v[210:211], off
	s_waitcnt vmcnt(8)
	s_waitcnt lgkmcnt(0)
	v_mfma_f32_16x16x32_bf16 v[64:67], v[132:135], v[164:167], v[64:67]
	v_mfma_f32_16x16x32_bf16 v[60:63], v[140:143], v[164:167], v[60:63]
	v_mfma_f32_16x16x32_bf16 v[52:55], v[132:135], v[172:175], v[52:55]
	v_mfma_f32_16x16x32_bf16 v[44:47], v[140:143], v[172:175], v[44:47]
	v_mfma_f32_16x16x32_bf16 v[36:39], v[132:135], v[180:183], v[36:39]
	v_mfma_f32_16x16x32_bf16 v[24:27], v[140:143], v[180:183], v[24:27]
	v_mfma_f32_16x16x32_bf16 v[16:19], v[132:135], v[188:191], v[16:19]
	v_mfma_f32_16x16x32_bf16 v[8:11], v[140:143], v[188:191], v[8:11]
	s_barrier
	s_setprio 1
	v_mfma_f32_16x16x32_bf16 v[64:67], v[136:139], v[168:171], v[64:67]
	v_mfma_f32_16x16x32_bf16 v[60:63], v[144:147], v[168:171], v[60:63]
	v_mfma_f32_16x16x32_bf16 v[52:55], v[136:139], v[176:179], v[52:55]
	v_mfma_f32_16x16x32_bf16 v[44:47], v[144:147], v[176:179], v[44:47]
	v_mfma_f32_16x16x32_bf16 v[36:39], v[136:139], v[184:187], v[36:39]
	v_mfma_f32_16x16x32_bf16 v[24:27], v[144:147], v[184:187], v[24:27]
	v_mfma_f32_16x16x32_bf16 v[16:19], v[136:139], v[192:195], v[16:19]
	v_mfma_f32_16x16x32_bf16 v[8:11], v[144:147], v[192:195], v[8:11]
	s_setprio 0
	s_setprio 1
	v_mfma_f32_16x16x32_bf16 v[56:59], v[148:151], v[164:167], v[56:59]
	v_mfma_f32_16x16x32_bf16 v[48:51], v[156:159], v[164:167], v[48:51]
	v_mfma_f32_16x16x32_bf16 v[40:43], v[148:151], v[172:175], v[40:43]
	v_mfma_f32_16x16x32_bf16 v[28:31], v[156:159], v[172:175], v[28:31]
	v_mfma_f32_16x16x32_bf16 v[20:23], v[148:151], v[180:183], v[20:23]
	v_mfma_f32_16x16x32_bf16 v[12:15], v[156:159], v[180:183], v[12:15]
	v_mfma_f32_16x16x32_bf16 v[4:7], v[148:151], v[188:191], v[4:7]
	v_mfma_f32_16x16x32_bf16 v[0:3], v[156:159], v[188:191], v[0:3]
	v_mfma_f32_16x16x32_bf16 v[56:59], v[152:155], v[168:171], v[56:59]
	v_mfma_f32_16x16x32_bf16 v[48:51], v[160:163], v[168:171], v[48:51]
	v_mfma_f32_16x16x32_bf16 v[40:43], v[152:155], v[176:179], v[40:43]
	v_mfma_f32_16x16x32_bf16 v[28:31], v[160:163], v[176:179], v[28:31]
	v_mfma_f32_16x16x32_bf16 v[20:23], v[152:155], v[184:187], v[20:23]
	v_mfma_f32_16x16x32_bf16 v[12:15], v[160:163], v[184:187], v[12:15]
	v_mfma_f32_16x16x32_bf16 v[4:7], v[152:155], v[192:195], v[4:7]
	v_mfma_f32_16x16x32_bf16 v[0:3], v[160:163], v[192:195], v[0:3]
	s_setprio 0
	s_barrier
	s_add_i32 s64, s64, 2
	s_add_u32 s0, s0, 0x100
	s_addc_u32 s1, s1, 0
	s_add_u32 s62, s62, 0x100
	s_addc_u32 s63, s63, 0
	s_cmp_gt_u32 s64, 5
	s_cbranch_scc0 .LBB0_49
	s_and_b64 vcc, exec, s[12:13]
	s_cbranch_vccz .LBB0_52
	s_barrier

; #define PG8_STAGE(bufoff, gbase, voff) do { _Pragma("unroll") for (int _i = 0; _i < 2; ++_i) \
;         __builtin_amdgcn_global_load_lds((const unsigned*)((const char*)(gbase) + (voff)[_i]), (PG8_LAS unsigned*)(lds + (bufoff) + ldsw + _i * 8192), 16, 0, 0); } while (0)
; #define PG8_LDA(dst, b, h) do { _Pragma("unroll") for (int m = 0; m < 4; ++m) _Pragma("unroll") for (int k = 0; k < 2; ++k) dst[m][k] = *(const PG8_LAS bf16x8*)(lds + PG8_SA(b, h) + aoff + m * 2048 + k * 1024); } while (0)
; #define PG8_LDB(dst, b, h) do { _Pragma("unroll") for (int n = 0; n < 2; ++n) _Pragma("unroll") for (int k = 0; k < 2; ++k) dst[n][k] = *(const PG8_LAS bf16x8*)(lds + PG8_SB(b, h) + boff + n * 2048 + k * 1024); } while (0)
; #define PG8_MMA(ai, bj, At, Bt) do { __builtin_amdgcn_s_setprio(1); _Pragma("unroll") for (int m = 0; m < 4; ++m) _Pragma("unroll") for (int n = 0; n < 2; ++n) _Pragma("unroll") for (int k = 0; k < 2; ++k) \
;         acc[ai][bj][m][n] = __builtin_amdgcn_mfma_f32_16x16x32_bf16(Bt[n][k], At[m][k], acc[ai][bj][m][n], 0, 0, 0); __builtin_amdgcn_s_setprio(0); } while (0)
; #define PG8_WAIT_V(n) asm volatile("s_waitcnt vmcnt(" #n ")" ::: "memory")
; #define PG8_WAIT_L(n) asm volatile("s_waitcnt lgkmcnt(" #n ")" ::: "memory")
; template <class Epi, class Sched, bool ALIGN_EPI = false, bool SP2 = false>
; __device__ __forceinline__ void gemm_phase(PG8_LAS unsigned char* lds, const Gemm g, const Sched& S, const Epi& E) {
;     ...
;             const bool last = (t == nt - 2);
;             const char* a1 = cA + (size_t)(t + 1) * kstep;
;             const char* a2 = last ? nA : cA + (size_t)(t + 2) * kstep; const char* b2 = last ? nB : cB + (size_t)(t + 2) * kstep;
;             const char* a3 = a2 + kstep; const char* b3 = b2 + kstep;
;             if (last && has_next) S.a_ready(nxt);
;             if constexpr (SP2) {
;             PG8_LDB(B0, 0, 0); PG8_LDB(B1, 0, 1); PG8_SCHED; PG8_LDA(At, 0, 0); PG8_STAGE(PG8_SA(1, 1), a1 + hstep, voffA);
;             PG8_WAIT_V(8); PG8_WAIT_L(0); PG8_BAR; PG8_MMA(0, 0, At, B0); PG8_MMA(0, 1, At, B1); PG8_BAR; PG8_SCHED;
;             PG8_LDA(At, 0, 1); PG8_STAGE(PG8_SB(0, 0), b2, voffB); PG8_STAGE(PG8_SB(0, 1), b2 + hstep, voffB); PG8_STAGE(PG8_SA(0, 0), a2, voffA);
;             PG8_WAIT_V(8); PG8_WAIT_L(0); PG8_BAR; PG8_MMA(1, 0, At, B0); PG8_MMA(1, 1, At, B1); PG8_BAR; PG8_SCHED;
.LBB0_342:
	s_add_u32 s4, s0, 0xfffc0080
	s_addc_u32 s5, s1, -1
	s_add_i32 s60, 0, 0x10000
	s_cmp_eq_u32 s59, 12
	s_cselect_b32 s43, s21, s5
	s_cselect_b32 s42, s45, s4
	s_cselect_b32 s5, s19, s58
	s_cselect_b32 s4, s46, s47
	s_add_i32 s62, 0, 0x14000
	v_add_u32_e32 v144, s60, v170
	v_add_u32_e32 v174, s62, v170
	ds_read_b128 v[132:135], v144
	ds_read_b128 v[136:139], v144 offset:1024
	ds_read_b128 v[140:143], v144 offset:2048
	ds_read_b128 v[144:147], v144 offset:3072
	ds_read_b128 v[158:161], v174
	ds_read_b128 v[162:165], v174 offset:1024
	ds_read_b128 v[166:169], v174 offset:2048
	ds_read_b128 v[174:177], v174 offset:3072
	v_lshl_add_u64 v[194:195], s[0:1], 0, v[154:155]
	s_add_i32 m0, s50, 0xc000
	ds_read_b128 v[178:181], v173
	ds_read_b128 v[182:185], v173 offset:1024
	ds_read_b128 v[186:189], v173 offset:2048
	ds_read_b128 v[190:193], v173 offset:3072
	ds_read_b128 v[202:205], v173 offset:4096
	ds_read_b128 v[206:209], v173 offset:5120
	ds_read_b128 v[210:213], v173 offset:6144
	ds_read_b128 v[214:217], v173 offset:7168
	global_load_lds_dwordx4 v[194:195], off
	v_lshl_add_u64 v[194:195], s[0:1], 0, v[156:157]
	s_add_i32 m0, s50, 0xe000
	s_nop 0
	global_load_lds_dwordx4 v[194:195], off
	s_waitcnt vmcnt(8)
	s_waitcnt lgkmcnt(0)
	v_mfma_f32_16x16x32_bf16 v[128:131], v[132:135], v[178:181], v[128:131]
	v_mfma_f32_16x16x32_bf16 v[124:127], v[140:143], v[178:181], v[124:127]
	v_mfma_f32_16x16x32_bf16 v[112:115], v[132:135], v[186:189], v[112:115]
	v_mfma_f32_16x16x32_bf16 v[108:111], v[140:143], v[186:189], v[108:111]
	v_mfma_f32_16x16x32_bf16 v[96:99], v[132:135], v[202:205], v[96:99]
	v_mfma_f32_16x16x32_bf16 v[92:95], v[140:143], v[202:205], v[92:95]
	v_mfma_f32_16x16x32_bf16 v[80:83], v[132:135], v[210:213], v[80:83]
	v_mfma_f32_16x16x32_bf16 v[76:79], v[140:143], v[210:213], v[76:79]
	s_barrier
	s_setprio 1
	v_mfma_f32_16x16x32_bf16 v[128:131], v[136:139], v[182:185], v[128:131]
	v_mfma_f32_16x16x32_bf16 v[124:127], v[144:147], v[182:185], v[124:127]
	v_mfma_f32_16x16x32_bf16 v[112:115], v[136:139], v[190:193], v[112:115]
	v_mfma_f32_16x16x32_bf16 v[108:111], v[144:147], v[190:193], v[108:111]
	v_mfma_f32_16x16x32_bf16 v[96:99], v[136:139], v[206:209], v[96:99]
	v_mfma_f32_16x16x32_bf16 v[92:95], v[144:147], v[206:209], v[92:95]
	v_mfma_f32_16x16x32_bf16 v[80:83], v[136:139], v[214:217], v[80:83]
	v_mfma_f32_16x16x32_bf16 v[76:79], v[144:147], v[214:217], v[76:79]
	s_setprio 0
	s_setprio 1
	v_mfma_f32_16x16x32_bf16 v[120:123], v[158:161], v[178:181], v[120:123]
	v_mfma_f32_16x16x32_bf16 v[116:119], v[166:169], v[178:181], v[116:119]
	v_mfma_f32_16x16x32_bf16 v[104:107], v[158:161], v[186:189], v[104:107]
	v_mfma_f32_16x16x32_bf16 v[100:103], v[166:169], v[186:189], v[100:103]
	v_mfma_f32_16x16x32_bf16 v[88:91], v[158:161], v[202:205], v[88:91]
	v_mfma_f32_16x16x32_bf16 v[84:87], v[166:169], v[202:205], v[84:87]
	v_mfma_f32_16x16x32_bf16 v[72:75], v[158:161], v[210:213], v[72:75]
	v_mfma_f32_16x16x32_bf16 v[68:71], v[166:169], v[210:213], v[68:71]
	v_mfma_f32_16x16x32_bf16 v[120:123], v[162:165], v[182:185], v[120:123]
	v_mfma_f32_16x16x32_bf16 v[116:119], v[174:177], v[182:185], v[116:119]
	v_mfma_f32_16x16x32_bf16 v[104:107], v[162:165], v[190:193], v[104:107]
	v_mfma_f32_16x16x32_bf16 v[100:103], v[174:177], v[190:193], v[100:103]
	v_mfma_f32_16x16x32_bf16 v[88:91], v[162:165], v[206:209], v[88:91]
	v_mfma_f32_16x16x32_bf16 v[84:87], v[174:177], v[206:209], v[84:87]
	v_mfma_f32_16x16x32_bf16 v[72:75], v[162:165], v[214:217], v[72:75]
	v_mfma_f32_16x16x32_bf16 v[68:71], v[174:177], v[214:217], v[68:71]
	s_setprio 0
	s_barrier
	s_add_i32 s60, s60, s49
	v_lshl_add_u64 v[194:195], s[4:5], 0, v[150:151]
	s_mov_b32 m0, s60
	ds_read_b128 v[178:181], v173 offset:16384
	ds_read_b128 v[182:185], v173 offset:17408
	ds_read_b128 v[186:189], v173 offset:18432
	ds_read_b128 v[190:193], v173 offset:19456
	ds_read_b128 v[202:205], v173 offset:20480
	ds_read_b128 v[206:209], v173 offset:21504
	ds_read_b128 v[210:213], v173 offset:22528
	ds_read_b128 v[214:217], v173 offset:23552
	global_load_lds_dwordx4 v[194:195], off
	s_add_i32 m0, s60, 0x2000
	s_add_u32 s60, s4, 0x40000
	v_lshl_add_u64 v[218:219], s[4:5], 0, v[32:33]
	s_addc_u32 s61, s5, 0
	s_add_i32 s62, s62, s49
	global_load_lds_dwordx4 v[218:219], off
	v_lshl_add_u64 v[220:221], s[60:61], 0, v[150:151]
	s_mov_b32 m0, s62
	v_lshl_add_u64 v[222:223], s[42:43], 0, v[148:149]
	global_load_lds_dwordx4 v[220:221], off
	v_lshl_add_u64 v[220:221], s[60:61], 0, v[32:33]
	s_add_i32 m0, s62, 0x2000
	s_nop 0
	global_load_lds_dwordx4 v[220:221], off
	v_lshl_add_u64 v[220:221], s[42:43], 0, v[152:153]
	s_mov_b32 m0, s50
	s_nop 0
	global_load_lds_dwordx4 v[220:221], off
	s_mov_b32 m0, s51
	s_nop 0
	global_load_lds_dwordx4 v[222:223], off
	s_waitcnt vmcnt(8)
	s_waitcnt lgkmcnt(0)
	v_mfma_f32_16x16x32_bf16 v[64:67], v[132:135], v[178:181], v[64:67]
	v_mfma_f32_16x16x32_bf16 v[60:63], v[140:143], v[178:181], v[60:63]
	v_mfma_f32_16x16x32_bf16 v[48:51], v[132:135], v[186:189], v[48:51]
	v_mfma_f32_16x16x32_bf16 v[44:47], v[140:143], v[186:189], v[44:47]
	v_mfma_f32_16x16x32_bf16 v[28:31], v[132:135], v[202:205], v[28:31]
	v_mfma_f32_16x16x32_bf16 v[24:27], v[140:143], v[202:205], v[24:27]
	v_mfma_f32_16x16x32_bf16 v[12:15], v[132:135], v[210:213], v[12:15]
	v_mfma_f32_16x16x32_bf16 v[8:11], v[140:143], v[210:213], v[8:11]
	s_barrier
; #define PG8_STAGE(bufoff, gbase, voff) do { _Pragma("unroll") for (int _i = 0; _i < 2; ++_i) \
;         __builtin_amdgcn_global_load_lds((const unsigned*)((const char*)(gbase) + (voff)[_i]), (PG8_LAS unsigned*)(lds + (bufoff) + ldsw + _i * 8192), 16, 0, 0); } while (0)
; #define PG8_LDA(dst, b, h) do { _Pragma("unroll") for (int m = 0; m < 4; ++m) _Pragma("unroll") for (int k = 0; k < 2; ++k) dst[m][k] = *(const PG8_LAS bf16x8*)(lds + PG8_SA(b, h) + aoff + m * 2048 + k * 1024); } while (0)
; #define PG8_LDB(dst, b, h) do { _Pragma("unroll") for (int n = 0; n < 2; ++n) _Pragma("unroll") for (int k = 0; k < 2; ++k) dst[n][k] = *(const PG8_LAS bf16x8*)(lds + PG8_SB(b, h) + boff + n * 2048 + k * 1024); } while (0)
; #define PG8_MMA(ai, bj, At, Bt) do { __builtin_amdgcn_s_setprio(1); _Pragma("unroll") for (int m = 0; m < 4; ++m) _Pragma("unroll") for (int n = 0; n < 2; ++n) _Pragma("unroll") for (int k = 0; k < 2; ++k) \
;         acc[ai][bj][m][n] = __builtin_amdgcn_mfma_f32_16x16x32_bf16(Bt[n][k], At[m][k], acc[ai][bj][m][n], 0, 0, 0); __builtin_amdgcn_s_setprio(0); } while (0)
; #define PG8_WAIT_V(n) asm volatile("s_waitcnt vmcnt(" #n ")" ::: "memory")
; #define PG8_WAIT_L(n) asm volatile("s_waitcnt lgkmcnt(" #n ")" ::: "memory")
; #define PG8_BAR __builtin_amdgcn_s_barrier()
; #define PG8_SCHED __builtin_amdgcn_sched_barrier(0)
; template <class Epi, class Sched, bool ALIGN_EPI = false, bool SP2 = false>
; __device__ __forceinline__ void gemm_phase(PG8_LAS unsigned char* lds, const Gemm g, const Sched& S, const Epi& E) {
;     ...
;             PG8_WAIT_V(8); PG8_WAIT_L(0); PG8_BAR; PG8_MMA(1, 0, At, B0); PG8_MMA(1, 1, At, B1); PG8_BAR; PG8_SCHED;
;             PG8_LDB(B0, 1, 0); PG8_LDB(B1, 1, 1); PG8_SCHED; PG8_LDA(At, 1, 0); PG8_STAGE(PG8_SA(0, 1), a2 + hstep, voffA);
;             PG8_WAIT_V(8); PG8_WAIT_L(0); PG8_BAR; PG8_MMA(0, 0, At, B0); PG8_MMA(0, 1, At, B1); PG8_BAR; PG8_SCHED;
	s_setprio 1
	v_mfma_f32_16x16x32_bf16 v[64:67], v[136:139], v[182:185], v[64:67]
	v_mfma_f32_16x16x32_bf16 v[60:63], v[144:147], v[182:185], v[60:63]
	v_mfma_f32_16x16x32_bf16 v[48:51], v[136:139], v[190:193], v[48:51]
	v_mfma_f32_16x16x32_bf16 v[44:47], v[144:147], v[190:193], v[44:47]
	v_mfma_f32_16x16x32_bf16 v[28:31], v[136:139], v[206:209], v[28:31]
	v_mfma_f32_16x16x32_bf16 v[24:27], v[144:147], v[206:209], v[24:27]
	v_mfma_f32_16x16x32_bf16 v[12:15], v[136:139], v[214:217], v[12:15]
	v_mfma_f32_16x16x32_bf16 v[8:11], v[144:147], v[214:217], v[8:11]
	s_setprio 0
	s_setprio 1
	v_mfma_f32_16x16x32_bf16 v[56:59], v[158:161], v[178:181], v[56:59]
	v_mfma_f32_16x16x32_bf16 v[52:55], v[166:169], v[178:181], v[52:55]
	v_mfma_f32_16x16x32_bf16 v[40:43], v[158:161], v[186:189], v[40:43]
	v_mfma_f32_16x16x32_bf16 v[36:39], v[166:169], v[186:189], v[36:39]
	v_mfma_f32_16x16x32_bf16 v[20:23], v[158:161], v[202:205], v[20:23]
	v_mfma_f32_16x16x32_bf16 v[16:19], v[166:169], v[202:205], v[16:19]
	v_mfma_f32_16x16x32_bf16 v[4:7], v[158:161], v[210:213], v[4:7]
	v_mfma_f32_16x16x32_bf16 v[0:3], v[166:169], v[210:213], v[0:3]
	v_mfma_f32_16x16x32_bf16 v[56:59], v[162:165], v[182:185], v[56:59]
	v_mfma_f32_16x16x32_bf16 v[52:55], v[174:177], v[182:185], v[52:55]
	v_mfma_f32_16x16x32_bf16 v[40:43], v[162:165], v[190:193], v[40:43]
	v_mfma_f32_16x16x32_bf16 v[36:39], v[174:177], v[190:193], v[36:39]
	v_mfma_f32_16x16x32_bf16 v[20:23], v[162:165], v[206:209], v[20:23]
	v_mfma_f32_16x16x32_bf16 v[16:19], v[174:177], v[206:209], v[16:19]
	v_mfma_f32_16x16x32_bf16 v[4:7], v[162:165], v[214:217], v[4:7]
	v_mfma_f32_16x16x32_bf16 v[0:3], v[174:177], v[214:217], v[0:3]
	s_setprio 0
	s_barrier
	s_add_i32 s60, 0, 0x18000
	s_add_i32 s61, 0, 0x1c000
	v_add_u32_e32 v144, s60, v170
	v_add_u32_e32 v174, s61, v170
	ds_read_b128 v[132:135], v144
	ds_read_b128 v[136:139], v144 offset:1024
	ds_read_b128 v[140:143], v144 offset:2048
	ds_read_b128 v[144:147], v144 offset:3072
	ds_read_b128 v[158:161], v174
	ds_read_b128 v[162:165], v174 offset:1024
	ds_read_b128 v[166:169], v174 offset:2048
	ds_read_b128 v[174:177], v174 offset:3072
	s_add_u32 s42, s42, 0x40000
	s_addc_u32 s43, s43, 0
	s_mov_b32 m0, s52
	v_lshl_add_u64 v[224:225], s[42:43], 0, v[152:153]
	ds_read_b128 v[178:181], v173 offset:32768
	ds_read_b128 v[182:185], v173 offset:33792
	ds_read_b128 v[186:189], v173 offset:34816
	ds_read_b128 v[190:193], v173 offset:35840
	ds_read_b128 v[202:205], v173 offset:36864
	ds_read_b128 v[206:209], v173 offset:37888
	ds_read_b128 v[210:213], v173 offset:38912
	ds_read_b128 v[214:217], v173 offset:39936
	global_load_lds_dwordx4 v[224:225], off
	v_lshl_add_u64 v[224:225], s[42:43], 0, v[148:149]
	s_mov_b32 m0, s53
	s_nop 0
	global_load_lds_dwordx4 v[224:225], off
	s_waitcnt vmcnt(8)
	s_waitcnt lgkmcnt(0)
	v_mfma_f32_16x16x32_bf16 v[128:131], v[132:135], v[178:181], v[128:131]
	v_mfma_f32_16x16x32_bf16 v[124:127], v[140:143], v[178:181], v[124:127]
	v_mfma_f32_16x16x32_bf16 v[112:115], v[132:135], v[186:189], v[112:115]
	v_mfma_f32_16x16x32_bf16 v[108:111], v[140:143], v[186:189], v[108:111]
	v_mfma_f32_16x16x32_bf16 v[96:99], v[132:135], v[202:205], v[96:99]
	v_mfma_f32_16x16x32_bf16 v[92:95], v[140:143], v[202:205], v[92:95]
	v_mfma_f32_16x16x32_bf16 v[80:83], v[132:135], v[210:213], v[80:83]
	v_mfma_f32_16x16x32_bf16 v[76:79], v[140:143], v[210:213], v[76:79]
	s_barrier
	s_setprio 1
	v_mfma_f32_16x16x32_bf16 v[128:131], v[136:139], v[182:185], v[128:131]
	v_mfma_f32_16x16x32_bf16 v[124:127], v[144:147], v[182:185], v[124:127]
	v_mfma_f32_16x16x32_bf16 v[112:115], v[136:139], v[190:193], v[112:115]
	v_mfma_f32_16x16x32_bf16 v[108:111], v[144:147], v[190:193], v[108:111]
	v_mfma_f32_16x16x32_bf16 v[96:99], v[136:139], v[206:209], v[96:99]
	v_mfma_f32_16x16x32_bf16 v[92:95], v[144:147], v[206:209], v[92:95]
	v_mfma_f32_16x16x32_bf16 v[80:83], v[136:139], v[214:217], v[80:83]
	v_mfma_f32_16x16x32_bf16 v[76:79], v[144:147], v[214:217], v[76:79]
	s_setprio 0
	s_setprio 1
	v_mfma_f32_16x16x32_bf16 v[120:123], v[158:161], v[178:181], v[120:123]
	v_mfma_f32_16x16x32_bf16 v[116:119], v[166:169], v[178:181], v[116:119]
	v_mfma_f32_16x16x32_bf16 v[104:107], v[158:161], v[186:189], v[104:107]
	v_mfma_f32_16x16x32_bf16 v[100:103], v[166:169], v[186:189], v[100:103]
	v_mfma_f32_16x16x32_bf16 v[88:91], v[158:161], v[202:205], v[88:91]
	v_mfma_f32_16x16x32_bf16 v[84:87], v[166:169], v[202:205], v[84:87]
	v_mfma_f32_16x16x32_bf16 v[72:75], v[158:161], v[210:213], v[72:75]
	v_mfma_f32_16x16x32_bf16 v[68:71], v[166:169], v[210:213], v[68:71]
	v_mfma_f32_16x16x32_bf16 v[120:123], v[162:165], v[182:185], v[120:123]
	v_mfma_f32_16x16x32_bf16 v[116:119], v[174:177], v[182:185], v[116:119]
	v_mfma_f32_16x16x32_bf16 v[104:107], v[162:165], v[190:193], v[104:107]
	v_mfma_f32_16x16x32_bf16 v[100:103], v[174:177], v[190:193], v[100:103]
	v_mfma_f32_16x16x32_bf16 v[88:91], v[162:165], v[206:209], v[88:91]
	v_mfma_f32_16x16x32_bf16 v[84:87], v[174:177], v[206:209], v[84:87]
	v_mfma_f32_16x16x32_bf16 v[72:75], v[162:165], v[214:217], v[72:75]
	v_mfma_f32_16x16x32_bf16 v[68:71], v[174:177], v[214:217], v[68:71]
	s_setprio 0
	s_barrier
; #define PG8_STAGE(bufoff, gbase, voff) do { _Pragma("unroll") for (int _i = 0; _i < 2; ++_i) \
;         __builtin_amdgcn_global_load_lds((const unsigned*)((const char*)(gbase) + (voff)[_i]), (PG8_LAS unsigned*)(lds + (bufoff) + ldsw + _i * 8192), 16, 0, 0); } while (0)
; #define PG8_LDA(dst, b, h) do { _Pragma("unroll") for (int m = 0; m < 4; ++m) _Pragma("unroll") for (int k = 0; k < 2; ++k) dst[m][k] = *(const PG8_LAS bf16x8*)(lds + PG8_SA(b, h) + aoff + m * 2048 + k * 1024); } while (0)
; #define PG8_MMA(ai, bj, At, Bt) do { __builtin_amdgcn_s_setprio(1); _Pragma("unroll") for (int m = 0; m < 4; ++m) _Pragma("unroll") for (int n = 0; n < 2; ++n) _Pragma("unroll") for (int k = 0; k < 2; ++k) \
;         acc[ai][bj][m][n] = __builtin_amdgcn_mfma_f32_16x16x32_bf16(Bt[n][k], At[m][k], acc[ai][bj][m][n], 0, 0, 0); __builtin_amdgcn_s_setprio(0); } while (0)
; #define PG8_WAIT_V(n) asm volatile("s_waitcnt vmcnt(" #n ")" ::: "memory")
; #define PG8_WAIT_L(n) asm volatile("s_waitcnt lgkmcnt(" #n ")" ::: "memory")
; #define PG8_BAR __builtin_amdgcn_s_barrier()
; #define PG8_SCHED __builtin_amdgcn_sched_barrier(0)
; template <class Epi, class Sched, bool ALIGN_EPI = false, bool SP2 = false>
; __device__ __forceinline__ void gemm_phase(PG8_LAS unsigned char* lds, const Gemm g, const Sched& S, const Epi& E) {
;     ...
;         for (int t = 0; t < nt; t += 2) {
;     ...
;             PG8_LDA(At, 1, 1); PG8_STAGE(PG8_SB(1, 0), b3, voffB); PG8_STAGE(PG8_SB(1, 1), b3 + hstep, voffB); PG8_STAGE(PG8_SA(1, 0), a3, voffA);
;             PG8_WAIT_V(8); PG8_WAIT_L(0); PG8_BAR; PG8_MMA(1, 0, At, B0); PG8_MMA(1, 1, At, B1); PG8_BAR; PG8_SCHED;
	s_add_i32 s42, s60, s49
	v_lshl_add_u64 v[194:195], v[194:195], 0, s[36:37]
	s_mov_b32 m0, s42
	ds_read_b128 v[178:181], v173 offset:49152
	ds_read_b128 v[182:185], v173 offset:50176
	ds_read_b128 v[186:189], v173 offset:51200
	ds_read_b128 v[190:193], v173 offset:52224
	ds_read_b128 v[202:205], v173 offset:53248
	ds_read_b128 v[206:209], v173 offset:54272
	ds_read_b128 v[210:213], v173 offset:55296
	ds_read_b128 v[214:217], v173 offset:56320
	global_load_lds_dwordx4 v[194:195], off
	s_add_i32 m0, s42, 0x2000
	s_add_u32 s4, s4, 0x40080
	v_lshl_add_u64 v[194:195], v[218:219], 0, s[36:37]
	s_addc_u32 s5, s5, 0
	s_add_i32 s42, s61, s49
	global_load_lds_dwordx4 v[194:195], off
	v_lshl_add_u64 v[194:195], s[4:5], 0, v[150:151]
	s_mov_b32 m0, s42
	s_nop 0
	global_load_lds_dwordx4 v[194:195], off
	v_lshl_add_u64 v[194:195], s[4:5], 0, v[32:33]
	s_add_i32 m0, s42, 0x2000
	s_nop 0
	global_load_lds_dwordx4 v[194:195], off
	v_lshl_add_u64 v[194:195], v[220:221], 0, s[36:37]
	s_mov_b32 m0, s54
	s_nop 0
	global_load_lds_dwordx4 v[194:195], off
	v_lshl_add_u64 v[194:195], v[222:223], 0, s[36:37]
	s_mov_b32 m0, s55
	s_nop 0
	global_load_lds_dwordx4 v[194:195], off
	s_waitcnt vmcnt(8)
	s_waitcnt lgkmcnt(0)
	v_mfma_f32_16x16x32_bf16 v[64:67], v[132:135], v[178:181], v[64:67]
	v_mfma_f32_16x16x32_bf16 v[60:63], v[140:143], v[178:181], v[60:63]
	v_mfma_f32_16x16x32_bf16 v[48:51], v[132:135], v[186:189], v[48:51]
	v_mfma_f32_16x16x32_bf16 v[44:47], v[140:143], v[186:189], v[44:47]
	v_mfma_f32_16x16x32_bf16 v[28:31], v[132:135], v[202:205], v[28:31]
	v_mfma_f32_16x16x32_bf16 v[24:27], v[140:143], v[202:205], v[24:27]
	v_mfma_f32_16x16x32_bf16 v[12:15], v[132:135], v[210:213], v[12:15]
	v_mfma_f32_16x16x32_bf16 v[8:11], v[140:143], v[210:213], v[8:11]
	s_barrier
	s_setprio 1
	v_mfma_f32_16x16x32_bf16 v[64:67], v[136:139], v[182:185], v[64:67]
	v_mfma_f32_16x16x32_bf16 v[60:63], v[144:147], v[182:185], v[60:63]
	v_mfma_f32_16x16x32_bf16 v[48:51], v[136:139], v[190:193], v[48:51]
	v_mfma_f32_16x16x32_bf16 v[44:47], v[144:147], v[190:193], v[44:47]
	v_mfma_f32_16x16x32_bf16 v[28:31], v[136:139], v[206:209], v[28:31]
	v_mfma_f32_16x16x32_bf16 v[24:27], v[144:147], v[206:209], v[24:27]
	v_mfma_f32_16x16x32_bf16 v[12:15], v[136:139], v[214:217], v[12:15]
	v_mfma_f32_16x16x32_bf16 v[8:11], v[144:147], v[214:217], v[8:11]
	s_setprio 0
	s_setprio 1
	v_mfma_f32_16x16x32_bf16 v[56:59], v[158:161], v[178:181], v[56:59]
	v_mfma_f32_16x16x32_bf16 v[52:55], v[166:169], v[178:181], v[52:55]
	v_mfma_f32_16x16x32_bf16 v[40:43], v[158:161], v[186:189], v[40:43]
	v_mfma_f32_16x16x32_bf16 v[36:39], v[166:169], v[186:189], v[36:39]
	v_mfma_f32_16x16x32_bf16 v[20:23], v[158:161], v[202:205], v[20:23]
	v_mfma_f32_16x16x32_bf16 v[16:19], v[166:169], v[202:205], v[16:19]
	v_mfma_f32_16x16x32_bf16 v[4:7], v[158:161], v[210:213], v[4:7]
	v_mfma_f32_16x16x32_bf16 v[0:3], v[166:169], v[210:213], v[0:3]
	v_mfma_f32_16x16x32_bf16 v[56:59], v[162:165], v[182:185], v[56:59]
	v_mfma_f32_16x16x32_bf16 v[52:55], v[174:177], v[182:185], v[52:55]
	v_mfma_f32_16x16x32_bf16 v[40:43], v[162:165], v[190:193], v[40:43]
	v_mfma_f32_16x16x32_bf16 v[36:39], v[174:177], v[190:193], v[36:39]
	v_mfma_f32_16x16x32_bf16 v[20:23], v[162:165], v[206:209], v[20:23]
	v_mfma_f32_16x16x32_bf16 v[16:19], v[174:177], v[206:209], v[16:19]
	v_mfma_f32_16x16x32_bf16 v[4:7], v[162:165], v[214:217], v[4:7]
	v_mfma_f32_16x16x32_bf16 v[0:3], v[174:177], v[214:217], v[0:3]
	s_setprio 0
	s_barrier
	s_add_i32 s59, s59, 2
	s_add_u32 s0, s0, 0x100
	s_addc_u32 s1, s1, 0
	s_add_u32 s47, s47, 0x100
	s_addc_u32 s58, s58, 0
	s_cmp_gt_u32 s59, 13
	s_cbranch_scc0 .LBB0_342
	s_and_b64 vcc, exec, s[16:17]
	s_cbranch_vccz .LBB0_345
	s_barrier

; #define PG8_STAGE(bufoff, gbase, voff) do { _Pragma("unroll") for (int _i = 0; _i < 2; ++_i) \
;         __builtin_amdgcn_global_load_lds((const unsigned*)((const char*)(gbase) + (voff)[_i]), (PG8_LAS unsigned*)(lds + (bufoff) + ldsw + _i * 8192), 16, 0, 0); } while (0)
; #define PG8_LDA(dst, b, h) do { _Pragma("unroll") for (int m = 0; m < 4; ++m) _Pragma("unroll") for (int k = 0; k < 2; ++k) dst[m][k] = *(const PG8_LAS bf16x8*)(lds + PG8_SA(b, h) + aoff + m * 2048 + k * 1024); } while (0)
; #define PG8_LDB(dst, b, h) do { _Pragma("unroll") for (int n = 0; n < 2; ++n) _Pragma("unroll") for (int k = 0; k < 2; ++k) dst[n][k] = *(const PG8_LAS bf16x8*)(lds + PG8_SB(b, h) + boff + n * 2048 + k * 1024); } while (0)
; #define PG8_MMA(ai, bj, At, Bt) do { __builtin_amdgcn_s_setprio(1); _Pragma("unroll") for (int m = 0; m < 4; ++m) _Pragma("unroll") for (int n = 0; n < 2; ++n) _Pragma("unroll") for (int k = 0; k < 2; ++k) \
;         acc[ai][bj][m][n] = __builtin_amdgcn_mfma_f32_16x16x32_bf16(Bt[n][k], At[m][k], acc[ai][bj][m][n], 0, 0, 0); __builtin_amdgcn_s_setprio(0); } while (0)
; #define PG8_WAIT_V(n) asm volatile("s_waitcnt vmcnt(" #n ")" ::: "memory")
; #define PG8_WAIT_L(n) asm volatile("s_waitcnt lgkmcnt(" #n ")" ::: "memory")
; template <class Epi, class Sched, bool ALIGN_EPI = false, bool SP2 = false>
; __device__ __forceinline__ void gemm_phase(PG8_LAS unsigned char* lds, const Gemm g, const Sched& S, const Epi& E) {
;     ...
;             const bool last = (t == nt - 2);
;             const char* a1 = cA + (size_t)(t + 1) * kstep;
;             const char* a2 = last ? nA : cA + (size_t)(t + 2) * kstep; const char* b2 = last ? nB : cB + (size_t)(t + 2) * kstep;
;             const char* a3 = a2 + kstep; const char* b3 = b2 + kstep;
;             if (last && has_next) S.a_ready(nxt);
;             if constexpr (SP2) {
;             PG8_LDB(B0, 0, 0); PG8_LDB(B1, 0, 1); PG8_SCHED; PG8_LDA(At, 0, 0); PG8_STAGE(PG8_SA(1, 1), a1 + hstep, voffA);
;             PG8_WAIT_V(8); PG8_WAIT_L(0); PG8_BAR; PG8_MMA(0, 0, At, B0); PG8_MMA(0, 1, At, B1); PG8_BAR; PG8_SCHED;
;             PG8_LDA(At, 0, 1); PG8_STAGE(PG8_SB(0, 0), b2, voffB); PG8_STAGE(PG8_SB(0, 1), b2 + hstep, voffB); PG8_STAGE(PG8_SA(0, 0), a2, voffA);
;             PG8_WAIT_V(8); PG8_WAIT_L(0); PG8_BAR; PG8_MMA(1, 0, At, B0); PG8_MMA(1, 1, At, B1); PG8_BAR; PG8_SCHED;
.LBB0_589:
	s_add_i32 s62, s40, 2
	s_add_u32 s63, s22, 0x80
	s_addc_u32 s41, s23, 0
	s_add_i32 s66, 0, 0x10000
	s_cmp_eq_u32 s56, s40
	s_cselect_b32 s41, s1, s41
	s_cselect_b32 s40, s0, s63
	s_cselect_b32 s65, s21, s61
	s_cselect_b32 s64, s20, s60
	s_add_i32 s63, 0, 0x14000
	v_add_u32_e32 v144, s66, v218
	v_add_u32_e32 v160, s63, v218
	ds_read_b128 v[132:135], v144
	ds_read_b128 v[136:139], v144 offset:1024
	ds_read_b128 v[140:143], v144 offset:2048
	ds_read_b128 v[144:147], v144 offset:3072
	ds_read_b128 v[148:151], v160
	ds_read_b128 v[152:155], v160 offset:1024
	ds_read_b128 v[156:159], v160 offset:2048
	ds_read_b128 v[160:163], v160 offset:3072
	v_lshl_add_u64 v[214:215], s[22:23], 0, v[202:203]
	s_add_i32 m0, s48, 0xc000
	ds_read_b128 v[164:167], v220
	ds_read_b128 v[168:171], v220 offset:1024
	ds_read_b128 v[172:175], v220 offset:2048
	ds_read_b128 v[176:179], v220 offset:3072
	ds_read_b128 v[180:183], v220 offset:4096
	ds_read_b128 v[184:187], v220 offset:5120
	ds_read_b128 v[206:209], v220 offset:6144
	ds_read_b128 v[210:213], v220 offset:7168
	global_load_lds_dwordx4 v[214:215], off
	v_lshl_add_u64 v[214:215], s[22:23], 0, v[204:205]
	s_add_i32 m0, s48, 0xe000
	s_nop 0
	global_load_lds_dwordx4 v[214:215], off
	s_waitcnt vmcnt(8)
	s_waitcnt lgkmcnt(0)
	v_mfma_f32_16x16x32_bf16 v[128:131], v[132:135], v[164:167], v[128:131]
	v_mfma_f32_16x16x32_bf16 v[124:127], v[140:143], v[164:167], v[124:127]
	v_mfma_f32_16x16x32_bf16 v[112:115], v[132:135], v[172:175], v[112:115]
	v_mfma_f32_16x16x32_bf16 v[108:111], v[140:143], v[172:175], v[108:111]
	v_mfma_f32_16x16x32_bf16 v[96:99], v[132:135], v[180:183], v[96:99]
	v_mfma_f32_16x16x32_bf16 v[92:95], v[140:143], v[180:183], v[92:95]
	v_mfma_f32_16x16x32_bf16 v[80:83], v[132:135], v[206:209], v[80:83]
	v_mfma_f32_16x16x32_bf16 v[76:79], v[140:143], v[206:209], v[76:79]
	s_barrier
	s_setprio 1
	v_mfma_f32_16x16x32_bf16 v[128:131], v[136:139], v[168:171], v[128:131]
	v_mfma_f32_16x16x32_bf16 v[124:127], v[144:147], v[168:171], v[124:127]
	v_mfma_f32_16x16x32_bf16 v[112:115], v[136:139], v[176:179], v[112:115]
	v_mfma_f32_16x16x32_bf16 v[108:111], v[144:147], v[176:179], v[108:111]
	v_mfma_f32_16x16x32_bf16 v[96:99], v[136:139], v[184:187], v[96:99]
	v_mfma_f32_16x16x32_bf16 v[92:95], v[144:147], v[184:187], v[92:95]
	v_mfma_f32_16x16x32_bf16 v[80:83], v[136:139], v[210:213], v[80:83]
	v_mfma_f32_16x16x32_bf16 v[76:79], v[144:147], v[210:213], v[76:79]
	s_setprio 0
	s_setprio 1
	v_mfma_f32_16x16x32_bf16 v[120:123], v[148:151], v[164:167], v[120:123]
	v_mfma_f32_16x16x32_bf16 v[116:119], v[156:159], v[164:167], v[116:119]
	v_mfma_f32_16x16x32_bf16 v[104:107], v[148:151], v[172:175], v[104:107]
	v_mfma_f32_16x16x32_bf16 v[100:103], v[156:159], v[172:175], v[100:103]
	v_mfma_f32_16x16x32_bf16 v[88:91], v[148:151], v[180:183], v[88:91]
	v_mfma_f32_16x16x32_bf16 v[84:87], v[156:159], v[180:183], v[84:87]
	v_mfma_f32_16x16x32_bf16 v[72:75], v[148:151], v[206:209], v[72:75]
	v_mfma_f32_16x16x32_bf16 v[68:71], v[156:159], v[206:209], v[68:71]
	v_mfma_f32_16x16x32_bf16 v[120:123], v[152:155], v[168:171], v[120:123]
	v_mfma_f32_16x16x32_bf16 v[116:119], v[160:163], v[168:171], v[116:119]
	v_mfma_f32_16x16x32_bf16 v[104:107], v[152:155], v[176:179], v[104:107]
	v_mfma_f32_16x16x32_bf16 v[100:103], v[160:163], v[176:179], v[100:103]
	v_mfma_f32_16x16x32_bf16 v[88:91], v[152:155], v[184:187], v[88:91]
	v_mfma_f32_16x16x32_bf16 v[84:87], v[160:163], v[184:187], v[84:87]
	v_mfma_f32_16x16x32_bf16 v[72:75], v[152:155], v[210:213], v[72:75]
	v_mfma_f32_16x16x32_bf16 v[68:71], v[160:163], v[210:213], v[68:71]
	s_setprio 0
	s_barrier
	s_add_i32 s66, s66, s47
	v_lshl_add_u64 v[214:215], s[64:65], 0, v[196:197]
	s_mov_b32 m0, s66
	ds_read_b128 v[164:167], v220 offset:16384
	ds_read_b128 v[168:171], v220 offset:17408
	ds_read_b128 v[172:175], v220 offset:18432
	ds_read_b128 v[176:179], v220 offset:19456
	ds_read_b128 v[180:183], v220 offset:20480
	ds_read_b128 v[184:187], v220 offset:21504
	ds_read_b128 v[206:209], v220 offset:22528
	ds_read_b128 v[210:213], v220 offset:23552
	global_load_lds_dwordx4 v[214:215], off
	s_add_i32 m0, s66, 0x2000
	v_lshl_add_u64 v[216:217], s[64:65], 0, v[32:33]
	s_add_u32 s64, s64, s4
	s_addc_u32 s65, s65, 0
	s_add_i32 s63, s63, s47
	global_load_lds_dwordx4 v[216:217], off
	v_lshl_add_u64 v[222:223], s[64:65], 0, v[196:197]
	s_mov_b32 m0, s63
	v_lshl_add_u64 v[224:225], s[64:65], 0, v[32:33]
	global_load_lds_dwordx4 v[222:223], off
	s_add_i32 m0, s63, 0x2000
	v_lshl_add_u64 v[226:227], s[40:41], 0, v[190:191]
	global_load_lds_dwordx4 v[224:225], off
	s_mov_b32 m0, s48
	v_lshl_add_u64 v[236:237], s[40:41], 0, v[188:189]
	global_load_lds_dwordx4 v[226:227], off
	s_mov_b32 m0, s49
	s_nop 0
	global_load_lds_dwordx4 v[236:237], off
	s_waitcnt vmcnt(8)
	s_waitcnt lgkmcnt(0)
	v_mfma_f32_16x16x32_bf16 v[64:67], v[132:135], v[164:167], v[64:67]
	v_mfma_f32_16x16x32_bf16 v[60:63], v[140:143], v[164:167], v[60:63]
	v_mfma_f32_16x16x32_bf16 v[48:51], v[132:135], v[172:175], v[48:51]
	v_mfma_f32_16x16x32_bf16 v[44:47], v[140:143], v[172:175], v[44:47]
	v_mfma_f32_16x16x32_bf16 v[28:31], v[132:135], v[180:183], v[28:31]
	v_mfma_f32_16x16x32_bf16 v[24:27], v[140:143], v[180:183], v[24:27]
	v_mfma_f32_16x16x32_bf16 v[12:15], v[132:135], v[206:209], v[12:15]
	v_mfma_f32_16x16x32_bf16 v[8:11], v[140:143], v[206:209], v[8:11]
	s_barrier
; #define PG8_STAGE(bufoff, gbase, voff) do { _Pragma("unroll") for (int _i = 0; _i < 2; ++_i) \
;         __builtin_amdgcn_global_load_lds((const unsigned*)((const char*)(gbase) + (voff)[_i]), (PG8_LAS unsigned*)(lds + (bufoff) + ldsw + _i * 8192), 16, 0, 0); } while (0)
; #define PG8_LDA(dst, b, h) do { _Pragma("unroll") for (int m = 0; m < 4; ++m) _Pragma("unroll") for (int k = 0; k < 2; ++k) dst[m][k] = *(const PG8_LAS bf16x8*)(lds + PG8_SA(b, h) + aoff + m * 2048 + k * 1024); } while (0)
; #define PG8_LDB(dst, b, h) do { _Pragma("unroll") for (int n = 0; n < 2; ++n) _Pragma("unroll") for (int k = 0; k < 2; ++k) dst[n][k] = *(const PG8_LAS bf16x8*)(lds + PG8_SB(b, h) + boff + n * 2048 + k * 1024); } while (0)
; #define PG8_MMA(ai, bj, At, Bt) do { __builtin_amdgcn_s_setprio(1); _Pragma("unroll") for (int m = 0; m < 4; ++m) _Pragma("unroll") for (int n = 0; n < 2; ++n) _Pragma("unroll") for (int k = 0; k < 2; ++k) \
;         acc[ai][bj][m][n] = __builtin_amdgcn_mfma_f32_16x16x32_bf16(Bt[n][k], At[m][k], acc[ai][bj][m][n], 0, 0, 0); __builtin_amdgcn_s_setprio(0); } while (0)
; #define PG8_WAIT_V(n) asm volatile("s_waitcnt vmcnt(" #n ")" ::: "memory")
; #define PG8_WAIT_L(n) asm volatile("s_waitcnt lgkmcnt(" #n ")" ::: "memory")
; #define PG8_BAR __builtin_amdgcn_s_barrier()
; #define PG8_SCHED __builtin_amdgcn_sched_barrier(0)
; template <class Epi, class Sched, bool ALIGN_EPI = false, bool SP2 = false>
; __device__ __forceinline__ void gemm_phase(PG8_LAS unsigned char* lds, const Gemm g, const Sched& S, const Epi& E) {
;     ...
;             PG8_WAIT_V(8); PG8_WAIT_L(0); PG8_BAR; PG8_MMA(1, 0, At, B0); PG8_MMA(1, 1, At, B1); PG8_BAR; PG8_SCHED;
;             PG8_LDB(B0, 1, 0); PG8_LDB(B1, 1, 1); PG8_SCHED; PG8_LDA(At, 1, 0); PG8_STAGE(PG8_SA(0, 1), a2 + hstep, voffA);
;             PG8_WAIT_V(8); PG8_WAIT_L(0); PG8_BAR; PG8_MMA(0, 0, At, B0); PG8_MMA(0, 1, At, B1); PG8_BAR; PG8_SCHED;
	s_setprio 1
	v_mfma_f32_16x16x32_bf16 v[64:67], v[136:139], v[168:171], v[64:67]
	v_mfma_f32_16x16x32_bf16 v[60:63], v[144:147], v[168:171], v[60:63]
	v_mfma_f32_16x16x32_bf16 v[48:51], v[136:139], v[176:179], v[48:51]
	v_mfma_f32_16x16x32_bf16 v[44:47], v[144:147], v[176:179], v[44:47]
	v_mfma_f32_16x16x32_bf16 v[28:31], v[136:139], v[184:187], v[28:31]
	v_mfma_f32_16x16x32_bf16 v[24:27], v[144:147], v[184:187], v[24:27]
	v_mfma_f32_16x16x32_bf16 v[12:15], v[136:139], v[210:213], v[12:15]
	v_mfma_f32_16x16x32_bf16 v[8:11], v[144:147], v[210:213], v[8:11]
	s_setprio 0
	s_setprio 1
	v_mfma_f32_16x16x32_bf16 v[56:59], v[148:151], v[164:167], v[56:59]
	v_mfma_f32_16x16x32_bf16 v[52:55], v[156:159], v[164:167], v[52:55]
	v_mfma_f32_16x16x32_bf16 v[40:43], v[148:151], v[172:175], v[40:43]
	v_mfma_f32_16x16x32_bf16 v[36:39], v[156:159], v[172:175], v[36:39]
	v_mfma_f32_16x16x32_bf16 v[20:23], v[148:151], v[180:183], v[20:23]
	v_mfma_f32_16x16x32_bf16 v[16:19], v[156:159], v[180:183], v[16:19]
	v_mfma_f32_16x16x32_bf16 v[4:7], v[148:151], v[206:209], v[4:7]
	v_mfma_f32_16x16x32_bf16 v[0:3], v[156:159], v[206:209], v[0:3]
	v_mfma_f32_16x16x32_bf16 v[56:59], v[152:155], v[168:171], v[56:59]
	v_mfma_f32_16x16x32_bf16 v[52:55], v[160:163], v[168:171], v[52:55]
	v_mfma_f32_16x16x32_bf16 v[40:43], v[152:155], v[176:179], v[40:43]
	v_mfma_f32_16x16x32_bf16 v[36:39], v[160:163], v[176:179], v[36:39]
	v_mfma_f32_16x16x32_bf16 v[20:23], v[152:155], v[184:187], v[20:23]
	v_mfma_f32_16x16x32_bf16 v[16:19], v[160:163], v[184:187], v[16:19]
	v_mfma_f32_16x16x32_bf16 v[4:7], v[152:155], v[210:213], v[4:7]
	v_mfma_f32_16x16x32_bf16 v[0:3], v[160:163], v[210:213], v[0:3]
	s_setprio 0
	s_barrier
	s_add_i32 s63, 0, 0x18000
	s_add_i32 s64, 0, 0x1c000
	v_add_u32_e32 v144, s63, v218
	v_add_u32_e32 v160, s64, v218
	ds_read_b128 v[132:135], v144
	ds_read_b128 v[136:139], v144 offset:1024
	ds_read_b128 v[140:143], v144 offset:2048
	ds_read_b128 v[144:147], v144 offset:3072
	ds_read_b128 v[148:151], v160
	ds_read_b128 v[152:155], v160 offset:1024
	ds_read_b128 v[156:159], v160 offset:2048
	ds_read_b128 v[160:163], v160 offset:3072
	s_add_u32 s40, s40, s4
	s_addc_u32 s41, s41, 0
	s_mov_b32 m0, s50
	v_lshl_add_u64 v[238:239], s[40:41], 0, v[190:191]
	ds_read_b128 v[164:167], v220 offset:32768
	ds_read_b128 v[168:171], v220 offset:33792
	ds_read_b128 v[172:175], v220 offset:34816
	ds_read_b128 v[176:179], v220 offset:35840
	ds_read_b128 v[180:183], v220 offset:36864
	ds_read_b128 v[184:187], v220 offset:37888
	ds_read_b128 v[206:209], v220 offset:38912
	ds_read_b128 v[210:213], v220 offset:39936
	global_load_lds_dwordx4 v[238:239], off
	v_lshl_add_u64 v[238:239], s[40:41], 0, v[188:189]
	s_mov_b32 m0, s51
	s_nop 0
	global_load_lds_dwordx4 v[238:239], off
	s_waitcnt vmcnt(8)
	s_waitcnt lgkmcnt(0)
	v_mfma_f32_16x16x32_bf16 v[128:131], v[132:135], v[164:167], v[128:131]
	v_mfma_f32_16x16x32_bf16 v[124:127], v[140:143], v[164:167], v[124:127]
	v_mfma_f32_16x16x32_bf16 v[112:115], v[132:135], v[172:175], v[112:115]
	v_mfma_f32_16x16x32_bf16 v[108:111], v[140:143], v[172:175], v[108:111]
	v_mfma_f32_16x16x32_bf16 v[96:99], v[132:135], v[180:183], v[96:99]
	v_mfma_f32_16x16x32_bf16 v[92:95], v[140:143], v[180:183], v[92:95]
	v_mfma_f32_16x16x32_bf16 v[80:83], v[132:135], v[206:209], v[80:83]
	v_mfma_f32_16x16x32_bf16 v[76:79], v[140:143], v[206:209], v[76:79]
	s_barrier
	s_setprio 1
	v_mfma_f32_16x16x32_bf16 v[128:131], v[136:139], v[168:171], v[128:131]
	v_mfma_f32_16x16x32_bf16 v[124:127], v[144:147], v[168:171], v[124:127]
	v_mfma_f32_16x16x32_bf16 v[112:115], v[136:139], v[176:179], v[112:115]
	v_mfma_f32_16x16x32_bf16 v[108:111], v[144:147], v[176:179], v[108:111]
	v_mfma_f32_16x16x32_bf16 v[96:99], v[136:139], v[184:187], v[96:99]
	v_mfma_f32_16x16x32_bf16 v[92:95], v[144:147], v[184:187], v[92:95]
	v_mfma_f32_16x16x32_bf16 v[80:83], v[136:139], v[210:213], v[80:83]
	v_mfma_f32_16x16x32_bf16 v[76:79], v[144:147], v[210:213], v[76:79]
	s_setprio 0
	s_setprio 1
	v_mfma_f32_16x16x32_bf16 v[120:123], v[148:151], v[164:167], v[120:123]
	v_mfma_f32_16x16x32_bf16 v[116:119], v[156:159], v[164:167], v[116:119]
	v_mfma_f32_16x16x32_bf16 v[104:107], v[148:151], v[172:175], v[104:107]
	v_mfma_f32_16x16x32_bf16 v[100:103], v[156:159], v[172:175], v[100:103]
	v_mfma_f32_16x16x32_bf16 v[88:91], v[148:151], v[180:183], v[88:91]
	v_mfma_f32_16x16x32_bf16 v[84:87], v[156:159], v[180:183], v[84:87]
	v_mfma_f32_16x16x32_bf16 v[72:75], v[148:151], v[206:209], v[72:75]
	v_mfma_f32_16x16x32_bf16 v[68:71], v[156:159], v[206:209], v[68:71]
	v_mfma_f32_16x16x32_bf16 v[120:123], v[152:155], v[168:171], v[120:123]
	v_mfma_f32_16x16x32_bf16 v[116:119], v[160:163], v[168:171], v[116:119]
	v_mfma_f32_16x16x32_bf16 v[104:107], v[152:155], v[176:179], v[104:107]
	v_mfma_f32_16x16x32_bf16 v[100:103], v[160:163], v[176:179], v[100:103]
	v_mfma_f32_16x16x32_bf16 v[88:91], v[152:155], v[184:187], v[88:91]
	v_mfma_f32_16x16x32_bf16 v[84:87], v[160:163], v[184:187], v[84:87]
	v_mfma_f32_16x16x32_bf16 v[72:75], v[152:155], v[210:213], v[72:75]
	v_mfma_f32_16x16x32_bf16 v[68:71], v[160:163], v[210:213], v[68:71]
	s_setprio 0
	s_barrier
; #define PG8_STAGE(bufoff, gbase, voff) do { _Pragma("unroll") for (int _i = 0; _i < 2; ++_i) \
;         __builtin_amdgcn_global_load_lds((const unsigned*)((const char*)(gbase) + (voff)[_i]), (PG8_LAS unsigned*)(lds + (bufoff) + ldsw + _i * 8192), 16, 0, 0); } while (0)
; #define PG8_LDA(dst, b, h) do { _Pragma("unroll") for (int m = 0; m < 4; ++m) _Pragma("unroll") for (int k = 0; k < 2; ++k) dst[m][k] = *(const PG8_LAS bf16x8*)(lds + PG8_SA(b, h) + aoff + m * 2048 + k * 1024); } while (0)
; #define PG8_MMA(ai, bj, At, Bt) do { __builtin_amdgcn_s_setprio(1); _Pragma("unroll") for (int m = 0; m < 4; ++m) _Pragma("unroll") for (int n = 0; n < 2; ++n) _Pragma("unroll") for (int k = 0; k < 2; ++k) \
;         acc[ai][bj][m][n] = __builtin_amdgcn_mfma_f32_16x16x32_bf16(Bt[n][k], At[m][k], acc[ai][bj][m][n], 0, 0, 0); __builtin_amdgcn_s_setprio(0); } while (0)
; #define PG8_WAIT_V(n) asm volatile("s_waitcnt vmcnt(" #n ")" ::: "memory")
; #define PG8_WAIT_L(n) asm volatile("s_waitcnt lgkmcnt(" #n ")" ::: "memory")
; #define PG8_BAR __builtin_amdgcn_s_barrier()
; #define PG8_SCHED __builtin_amdgcn_sched_barrier(0)
; template <class Epi, class Sched, bool ALIGN_EPI = false, bool SP2 = false>
; __device__ __forceinline__ void gemm_phase(PG8_LAS unsigned char* lds, const Gemm g, const Sched& S, const Epi& E) {
;     ...
;         for (int t = 0; t < nt; t += 2) {
;     ...
;             PG8_LDA(At, 1, 1); PG8_STAGE(PG8_SB(1, 0), b3, voffB); PG8_STAGE(PG8_SB(1, 1), b3 + hstep, voffB); PG8_STAGE(PG8_SA(1, 0), a3, voffA);
;             PG8_WAIT_V(8); PG8_WAIT_L(0); PG8_BAR; PG8_MMA(1, 0, At, B0); PG8_MMA(1, 1, At, B1); PG8_BAR; PG8_SCHED;
	s_add_i32 s40, s63, s47
	v_lshl_add_u64 v[214:215], v[214:215], 0, s[36:37]
	s_mov_b32 m0, s40
	ds_read_b128 v[164:167], v220 offset:49152
	ds_read_b128 v[168:171], v220 offset:50176
	ds_read_b128 v[172:175], v220 offset:51200
	ds_read_b128 v[176:179], v220 offset:52224
	ds_read_b128 v[180:183], v220 offset:53248
	ds_read_b128 v[184:187], v220 offset:54272
	ds_read_b128 v[206:209], v220 offset:55296
	ds_read_b128 v[210:213], v220 offset:56320
	global_load_lds_dwordx4 v[214:215], off
	v_lshl_add_u64 v[214:215], v[216:217], 0, s[36:37]
	s_add_i32 m0, s40, 0x2000
	s_add_i32 s40, s64, s47
	global_load_lds_dwordx4 v[214:215], off
	v_lshl_add_u64 v[214:215], v[222:223], 0, s[36:37]
	s_mov_b32 m0, s40
	s_nop 0
	global_load_lds_dwordx4 v[214:215], off
	v_lshl_add_u64 v[214:215], v[224:225], 0, s[36:37]
	s_add_i32 m0, s40, 0x2000
	s_nop 0
	global_load_lds_dwordx4 v[214:215], off
	v_lshl_add_u64 v[214:215], v[226:227], 0, s[36:37]
	s_mov_b32 m0, s52
	s_nop 0
	global_load_lds_dwordx4 v[214:215], off
	v_lshl_add_u64 v[214:215], v[236:237], 0, s[36:37]
	s_mov_b32 m0, s53
	s_nop 0
	global_load_lds_dwordx4 v[214:215], off
	s_waitcnt vmcnt(8)
	s_waitcnt lgkmcnt(0)
	v_mfma_f32_16x16x32_bf16 v[64:67], v[132:135], v[164:167], v[64:67]
	v_mfma_f32_16x16x32_bf16 v[60:63], v[140:143], v[164:167], v[60:63]
	v_mfma_f32_16x16x32_bf16 v[48:51], v[132:135], v[172:175], v[48:51]
	v_mfma_f32_16x16x32_bf16 v[44:47], v[140:143], v[172:175], v[44:47]
	v_mfma_f32_16x16x32_bf16 v[28:31], v[132:135], v[180:183], v[28:31]
	v_mfma_f32_16x16x32_bf16 v[24:27], v[140:143], v[180:183], v[24:27]
	v_mfma_f32_16x16x32_bf16 v[12:15], v[132:135], v[206:209], v[12:15]
	v_mfma_f32_16x16x32_bf16 v[8:11], v[140:143], v[206:209], v[8:11]
	s_barrier
	s_setprio 1
	v_mfma_f32_16x16x32_bf16 v[64:67], v[136:139], v[168:171], v[64:67]
	v_mfma_f32_16x16x32_bf16 v[60:63], v[144:147], v[168:171], v[60:63]
	v_mfma_f32_16x16x32_bf16 v[48:51], v[136:139], v[176:179], v[48:51]
	v_mfma_f32_16x16x32_bf16 v[44:47], v[144:147], v[176:179], v[44:47]
	v_mfma_f32_16x16x32_bf16 v[28:31], v[136:139], v[184:187], v[28:31]
	v_mfma_f32_16x16x32_bf16 v[24:27], v[144:147], v[184:187], v[24:27]
	v_mfma_f32_16x16x32_bf16 v[12:15], v[136:139], v[210:213], v[12:15]
	v_mfma_f32_16x16x32_bf16 v[8:11], v[144:147], v[210:213], v[8:11]
	s_setprio 0
	s_setprio 1
	v_mfma_f32_16x16x32_bf16 v[56:59], v[148:151], v[164:167], v[56:59]
	v_mfma_f32_16x16x32_bf16 v[52:55], v[156:159], v[164:167], v[52:55]
	v_mfma_f32_16x16x32_bf16 v[40:43], v[148:151], v[172:175], v[40:43]
	v_mfma_f32_16x16x32_bf16 v[36:39], v[156:159], v[172:175], v[36:39]
	v_mfma_f32_16x16x32_bf16 v[20:23], v[148:151], v[180:183], v[20:23]
	v_mfma_f32_16x16x32_bf16 v[16:19], v[156:159], v[180:183], v[16:19]
	v_mfma_f32_16x16x32_bf16 v[4:7], v[148:151], v[206:209], v[4:7]
	v_mfma_f32_16x16x32_bf16 v[0:3], v[156:159], v[206:209], v[0:3]
	v_mfma_f32_16x16x32_bf16 v[56:59], v[152:155], v[168:171], v[56:59]
	v_mfma_f32_16x16x32_bf16 v[52:55], v[160:163], v[168:171], v[52:55]
	v_mfma_f32_16x16x32_bf16 v[40:43], v[152:155], v[176:179], v[40:43]
	v_mfma_f32_16x16x32_bf16 v[36:39], v[160:163], v[176:179], v[36:39]
	v_mfma_f32_16x16x32_bf16 v[20:23], v[152:155], v[184:187], v[20:23]
	v_mfma_f32_16x16x32_bf16 v[16:19], v[160:163], v[184:187], v[16:19]
	v_mfma_f32_16x16x32_bf16 v[4:7], v[152:155], v[210:213], v[4:7]
	v_mfma_f32_16x16x32_bf16 v[0:3], v[160:163], v[210:213], v[0:3]
	s_setprio 0
	s_barrier
	s_add_u32 s22, s22, 0x100
	s_addc_u32 s23, s23, 0
	s_add_u32 s60, s60, 0x100
	s_addc_u32 s61, s61, 0
	s_cmp_ge_u32 s62, s55
	s_mov_b32 s40, s62
	s_cbranch_scc0 .LBB0_589
	s_and_b64 vcc, exec, s[16:17]
	s_cbranch_vccz .LBB0_592
	s_barrier

; #define PG8_STAGE(bufoff, gbase, voff) do { _Pragma("unroll") for (int _i = 0; _i < 2; ++_i) \
;         __builtin_amdgcn_global_load_lds((const unsigned*)((const char*)(gbase) + (voff)[_i]), (PG8_LAS unsigned*)(lds + (bufoff) + ldsw + _i * 8192), 16, 0, 0); } while (0)
; #define PG8_LDA(dst, b, h) do { _Pragma("unroll") for (int m = 0; m < 4; ++m) _Pragma("unroll") for (int k = 0; k < 2; ++k) dst[m][k] = *(const PG8_LAS bf16x8*)(lds + PG8_SA(b, h) + aoff + m * 2048 + k * 1024); } while (0)
; #define PG8_LDB(dst, b, h) do { _Pragma("unroll") for (int n = 0; n < 2; ++n) _Pragma("unroll") for (int k = 0; k < 2; ++k) dst[n][k] = *(const PG8_LAS bf16x8*)(lds + PG8_SB(b, h) + boff + n * 2048 + k * 1024); } while (0)
; #define PG8_MMA(ai, bj, At, Bt) do { __builtin_amdgcn_s_setprio(1); _Pragma("unroll") for (int m = 0; m < 4; ++m) _Pragma("unroll") for (int n = 0; n < 2; ++n) _Pragma("unroll") for (int k = 0; k < 2; ++k) \
;         acc[ai][bj][m][n] = __builtin_amdgcn_mfma_f32_16x16x32_bf16(Bt[n][k], At[m][k], acc[ai][bj][m][n], 0, 0, 0); __builtin_amdgcn_s_setprio(0); } while (0)
; #define PG8_WAIT_V(n) asm volatile("s_waitcnt vmcnt(" #n ")" ::: "memory")
; #define PG8_WAIT_L(n) asm volatile("s_waitcnt lgkmcnt(" #n ")" ::: "memory")
; template <class Epi, class Sched, bool ALIGN_EPI = false, bool SP2 = false>
; __device__ __forceinline__ void gemm_phase(PG8_LAS unsigned char* lds, const Gemm g, const Sched& S, const Epi& E) {
;     ...
;             const bool last = (t == nt - 2);
;             const char* a1 = cA + (size_t)(t + 1) * kstep;
;             const char* a2 = last ? nA : cA + (size_t)(t + 2) * kstep; const char* b2 = last ? nB : cB + (size_t)(t + 2) * kstep;
;             const char* a3 = a2 + kstep; const char* b3 = b2 + kstep;
;             if (last && has_next) S.a_ready(nxt);
;             if constexpr (SP2) {
;             PG8_LDB(B0, 0, 0); PG8_LDB(B1, 0, 1); PG8_SCHED; PG8_LDA(At, 0, 0); PG8_STAGE(PG8_SA(1, 1), a1 + hstep, voffA);
;             PG8_WAIT_V(8); PG8_WAIT_L(0); PG8_BAR; PG8_MMA(0, 0, At, B0); PG8_MMA(0, 1, At, B1); PG8_BAR; PG8_SCHED;
;             PG8_LDA(At, 0, 1); PG8_STAGE(PG8_SB(0, 0), b2, voffB); PG8_STAGE(PG8_SB(0, 1), b2 + hstep, voffB); PG8_STAGE(PG8_SA(0, 0), a2, voffA);
;             PG8_WAIT_V(8); PG8_WAIT_L(0); PG8_BAR; PG8_MMA(1, 0, At, B0); PG8_MMA(1, 1, At, B1); PG8_BAR; PG8_SCHED;
.LBB0_623:
	s_add_u32 s22, s0, 0xfffc0080
	s_addc_u32 s23, s1, -1
	s_add_i32 s58, 0, 0x10000
	s_cmp_eq_u32 s57, 12
	s_cselect_b32 s41, s17, s23
	s_cselect_b32 s40, s53, s22
	v_add_u32_e32 v144, s58, v147
	s_cselect_b32 s23, s15, s56
	s_cselect_b32 s22, s54, s55
	s_add_i32 s60, 0, 0x14000
	ds_read_b128 v[140:143], v144
	ds_read_b128 v[150:153], v144 offset:1024
	ds_read_b128 v[154:157], v144 offset:2048
	ds_read_b128 v[158:161], v144 offset:3072
	v_add_u32_e32 v144, s60, v147
	ds_read_b128 v[162:165], v144
	ds_read_b128 v[166:169], v144 offset:1024
	ds_read_b128 v[170:173], v144 offset:2048
	ds_read_b128 v[174:177], v144 offset:3072
	v_lshl_add_u64 v[144:145], s[0:1], 0, v[136:137]
	s_add_i32 m0, s44, 0xc000
	ds_read_b128 v[178:181], v149
	ds_read_b128 v[182:185], v149 offset:1024
	ds_read_b128 v[186:189], v149 offset:2048
	ds_read_b128 v[190:193], v149 offset:3072
	ds_read_b128 v[202:205], v149 offset:4096
	ds_read_b128 v[206:209], v149 offset:5120
	ds_read_b128 v[210:213], v149 offset:6144
	ds_read_b128 v[214:217], v149 offset:7168
	global_load_lds_dwordx4 v[144:145], off
	v_lshl_add_u64 v[144:145], s[0:1], 0, v[138:139]
	s_add_i32 m0, s44, 0xe000
	s_nop 0
	global_load_lds_dwordx4 v[144:145], off
	s_waitcnt vmcnt(8)
	s_waitcnt lgkmcnt(0)
	v_mfma_f32_16x16x32_bf16 v[128:131], v[140:143], v[178:181], v[128:131]
	v_mfma_f32_16x16x32_bf16 v[124:127], v[154:157], v[178:181], v[124:127]
	v_mfma_f32_16x16x32_bf16 v[112:115], v[140:143], v[186:189], v[112:115]
	v_mfma_f32_16x16x32_bf16 v[108:111], v[154:157], v[186:189], v[108:111]
	v_mfma_f32_16x16x32_bf16 v[96:99], v[140:143], v[202:205], v[96:99]
	v_mfma_f32_16x16x32_bf16 v[92:95], v[154:157], v[202:205], v[92:95]
	v_mfma_f32_16x16x32_bf16 v[80:83], v[140:143], v[210:213], v[80:83]
	v_mfma_f32_16x16x32_bf16 v[76:79], v[154:157], v[210:213], v[76:79]
	s_barrier
	s_setprio 1
	v_mfma_f32_16x16x32_bf16 v[128:131], v[150:153], v[182:185], v[128:131]
	v_mfma_f32_16x16x32_bf16 v[124:127], v[158:161], v[182:185], v[124:127]
	v_mfma_f32_16x16x32_bf16 v[112:115], v[150:153], v[190:193], v[112:115]
	v_mfma_f32_16x16x32_bf16 v[108:111], v[158:161], v[190:193], v[108:111]
	v_mfma_f32_16x16x32_bf16 v[96:99], v[150:153], v[206:209], v[96:99]
	v_mfma_f32_16x16x32_bf16 v[92:95], v[158:161], v[206:209], v[92:95]
	v_mfma_f32_16x16x32_bf16 v[80:83], v[150:153], v[214:217], v[80:83]
	v_mfma_f32_16x16x32_bf16 v[76:79], v[158:161], v[214:217], v[76:79]
	s_setprio 0
	s_setprio 1
	v_mfma_f32_16x16x32_bf16 v[120:123], v[162:165], v[178:181], v[120:123]
	v_mfma_f32_16x16x32_bf16 v[116:119], v[170:173], v[178:181], v[116:119]
	v_mfma_f32_16x16x32_bf16 v[104:107], v[162:165], v[186:189], v[104:107]
	v_mfma_f32_16x16x32_bf16 v[100:103], v[170:173], v[186:189], v[100:103]
	v_mfma_f32_16x16x32_bf16 v[88:91], v[162:165], v[202:205], v[88:91]
	v_mfma_f32_16x16x32_bf16 v[84:87], v[170:173], v[202:205], v[84:87]
	v_mfma_f32_16x16x32_bf16 v[72:75], v[162:165], v[210:213], v[72:75]
	v_mfma_f32_16x16x32_bf16 v[68:71], v[170:173], v[210:213], v[68:71]
	v_mfma_f32_16x16x32_bf16 v[120:123], v[166:169], v[182:185], v[120:123]
	v_mfma_f32_16x16x32_bf16 v[116:119], v[174:177], v[182:185], v[116:119]
	v_mfma_f32_16x16x32_bf16 v[104:107], v[166:169], v[190:193], v[104:107]
	v_mfma_f32_16x16x32_bf16 v[100:103], v[174:177], v[190:193], v[100:103]
	v_mfma_f32_16x16x32_bf16 v[88:91], v[166:169], v[206:209], v[88:91]
	v_mfma_f32_16x16x32_bf16 v[84:87], v[174:177], v[206:209], v[84:87]
	v_mfma_f32_16x16x32_bf16 v[72:75], v[166:169], v[214:217], v[72:75]
	v_mfma_f32_16x16x32_bf16 v[68:71], v[174:177], v[214:217], v[68:71]
	s_setprio 0
	s_barrier
	s_add_i32 s58, s58, s43
	v_lshl_add_u64 v[144:145], s[22:23], 0, v[196:197]
	s_mov_b32 m0, s58
	ds_read_b128 v[178:181], v149 offset:16384
	ds_read_b128 v[182:185], v149 offset:17408
	ds_read_b128 v[186:189], v149 offset:18432
	ds_read_b128 v[190:193], v149 offset:19456
	ds_read_b128 v[202:205], v149 offset:20480
	ds_read_b128 v[206:209], v149 offset:21504
	ds_read_b128 v[210:213], v149 offset:22528
	ds_read_b128 v[214:217], v149 offset:23552
	global_load_lds_dwordx4 v[144:145], off
	s_add_i32 m0, s58, 0x2000
	s_add_u32 s58, s22, 0x40000
	v_lshl_add_u64 v[194:195], s[22:23], 0, v[32:33]
	s_addc_u32 s59, s23, 0
	s_add_i32 s60, s60, s43
	global_load_lds_dwordx4 v[194:195], off
	v_lshl_add_u64 v[218:219], s[58:59], 0, v[196:197]
	s_mov_b32 m0, s60
	v_lshl_add_u64 v[220:221], s[40:41], 0, v[132:133]
	global_load_lds_dwordx4 v[218:219], off
	v_lshl_add_u64 v[218:219], s[58:59], 0, v[32:33]
	s_add_i32 m0, s60, 0x2000
	s_nop 0
	global_load_lds_dwordx4 v[218:219], off
	v_lshl_add_u64 v[218:219], s[40:41], 0, v[134:135]
	s_mov_b32 m0, s44
	s_nop 0
	global_load_lds_dwordx4 v[218:219], off
	s_mov_b32 m0, s45
	s_nop 0
	global_load_lds_dwordx4 v[220:221], off
	s_waitcnt vmcnt(8)
	s_waitcnt lgkmcnt(0)
	v_mfma_f32_16x16x32_bf16 v[64:67], v[140:143], v[178:181], v[64:67]
	v_mfma_f32_16x16x32_bf16 v[60:63], v[154:157], v[178:181], v[60:63]
	v_mfma_f32_16x16x32_bf16 v[48:51], v[140:143], v[186:189], v[48:51]
	v_mfma_f32_16x16x32_bf16 v[44:47], v[154:157], v[186:189], v[44:47]
	v_mfma_f32_16x16x32_bf16 v[28:31], v[140:143], v[202:205], v[28:31]
	v_mfma_f32_16x16x32_bf16 v[24:27], v[154:157], v[202:205], v[24:27]
	v_mfma_f32_16x16x32_bf16 v[12:15], v[140:143], v[210:213], v[12:15]
	v_mfma_f32_16x16x32_bf16 v[8:11], v[154:157], v[210:213], v[8:11]
	s_barrier
; #define PG8_STAGE(bufoff, gbase, voff) do { _Pragma("unroll") for (int _i = 0; _i < 2; ++_i) \
;         __builtin_amdgcn_global_load_lds((const unsigned*)((const char*)(gbase) + (voff)[_i]), (PG8_LAS unsigned*)(lds + (bufoff) + ldsw + _i * 8192), 16, 0, 0); } while (0)
; #define PG8_LDA(dst, b, h) do { _Pragma("unroll") for (int m = 0; m < 4; ++m) _Pragma("unroll") for (int k = 0; k < 2; ++k) dst[m][k] = *(const PG8_LAS bf16x8*)(lds + PG8_SA(b, h) + aoff + m * 2048 + k * 1024); } while (0)
; #define PG8_LDB(dst, b, h) do { _Pragma("unroll") for (int n = 0; n < 2; ++n) _Pragma("unroll") for (int k = 0; k < 2; ++k) dst[n][k] = *(const PG8_LAS bf16x8*)(lds + PG8_SB(b, h) + boff + n * 2048 + k * 1024); } while (0)
; #define PG8_MMA(ai, bj, At, Bt) do { __builtin_amdgcn_s_setprio(1); _Pragma("unroll") for (int m = 0; m < 4; ++m) _Pragma("unroll") for (int n = 0; n < 2; ++n) _Pragma("unroll") for (int k = 0; k < 2; ++k) \
;         acc[ai][bj][m][n] = __builtin_amdgcn_mfma_f32_16x16x32_bf16(Bt[n][k], At[m][k], acc[ai][bj][m][n], 0, 0, 0); __builtin_amdgcn_s_setprio(0); } while (0)
; #define PG8_WAIT_V(n) asm volatile("s_waitcnt vmcnt(" #n ")" ::: "memory")
; #define PG8_WAIT_L(n) asm volatile("s_waitcnt lgkmcnt(" #n ")" ::: "memory")
; #define PG8_BAR __builtin_amdgcn_s_barrier()
; #define PG8_SCHED __builtin_amdgcn_sched_barrier(0)
; template <class Epi, class Sched, bool ALIGN_EPI = false, bool SP2 = false>
; __device__ __forceinline__ void gemm_phase(PG8_LAS unsigned char* lds, const Gemm g, const Sched& S, const Epi& E) {
;     ...
;             PG8_WAIT_V(8); PG8_WAIT_L(0); PG8_BAR; PG8_MMA(1, 0, At, B0); PG8_MMA(1, 1, At, B1); PG8_BAR; PG8_SCHED;
;             PG8_LDB(B0, 1, 0); PG8_LDB(B1, 1, 1); PG8_SCHED; PG8_LDA(At, 1, 0); PG8_STAGE(PG8_SA(0, 1), a2 + hstep, voffA);
;             PG8_WAIT_V(8); PG8_WAIT_L(0); PG8_BAR; PG8_MMA(0, 0, At, B0); PG8_MMA(0, 1, At, B1); PG8_BAR; PG8_SCHED;
	s_setprio 1
	v_mfma_f32_16x16x32_bf16 v[64:67], v[150:153], v[182:185], v[64:67]
	v_mfma_f32_16x16x32_bf16 v[60:63], v[158:161], v[182:185], v[60:63]
	v_mfma_f32_16x16x32_bf16 v[48:51], v[150:153], v[190:193], v[48:51]
	v_mfma_f32_16x16x32_bf16 v[44:47], v[158:161], v[190:193], v[44:47]
	v_mfma_f32_16x16x32_bf16 v[28:31], v[150:153], v[206:209], v[28:31]
	v_mfma_f32_16x16x32_bf16 v[24:27], v[158:161], v[206:209], v[24:27]
	v_mfma_f32_16x16x32_bf16 v[12:15], v[150:153], v[214:217], v[12:15]
	v_mfma_f32_16x16x32_bf16 v[8:11], v[158:161], v[214:217], v[8:11]
	s_setprio 0
	s_setprio 1
	v_mfma_f32_16x16x32_bf16 v[56:59], v[162:165], v[178:181], v[56:59]
	v_mfma_f32_16x16x32_bf16 v[52:55], v[170:173], v[178:181], v[52:55]
	v_mfma_f32_16x16x32_bf16 v[40:43], v[162:165], v[186:189], v[40:43]
	v_mfma_f32_16x16x32_bf16 v[36:39], v[170:173], v[186:189], v[36:39]
	v_mfma_f32_16x16x32_bf16 v[20:23], v[162:165], v[202:205], v[20:23]
	v_mfma_f32_16x16x32_bf16 v[16:19], v[170:173], v[202:205], v[16:19]
	v_mfma_f32_16x16x32_bf16 v[4:7], v[162:165], v[210:213], v[4:7]
	v_mfma_f32_16x16x32_bf16 v[0:3], v[170:173], v[210:213], v[0:3]
	v_mfma_f32_16x16x32_bf16 v[56:59], v[166:169], v[182:185], v[56:59]
	v_mfma_f32_16x16x32_bf16 v[52:55], v[174:177], v[182:185], v[52:55]
	v_mfma_f32_16x16x32_bf16 v[40:43], v[166:169], v[190:193], v[40:43]
	v_mfma_f32_16x16x32_bf16 v[36:39], v[174:177], v[190:193], v[36:39]
	v_mfma_f32_16x16x32_bf16 v[20:23], v[166:169], v[206:209], v[20:23]
	v_mfma_f32_16x16x32_bf16 v[16:19], v[174:177], v[206:209], v[16:19]
	v_mfma_f32_16x16x32_bf16 v[4:7], v[166:169], v[214:217], v[4:7]
	v_mfma_f32_16x16x32_bf16 v[0:3], v[174:177], v[214:217], v[0:3]
	s_setprio 0
	s_barrier
	s_add_i32 s58, 0, 0x18000
	v_add_u32_e32 v146, s58, v147
	s_add_i32 s59, 0, 0x1c000
	ds_read_b128 v[140:143], v146
	ds_read_b128 v[150:153], v146 offset:1024
	ds_read_b128 v[154:157], v146 offset:2048
	ds_read_b128 v[158:161], v146 offset:3072
	v_add_u32_e32 v146, s59, v147
	ds_read_b128 v[162:165], v146
	ds_read_b128 v[166:169], v146 offset:1024
	ds_read_b128 v[170:173], v146 offset:2048
	ds_read_b128 v[174:177], v146 offset:3072
	s_add_u32 s40, s40, 0x40000
	s_addc_u32 s41, s41, 0
	s_mov_b32 m0, s46
	v_lshl_add_u64 v[222:223], s[40:41], 0, v[134:135]
	ds_read_b128 v[178:181], v149 offset:32768
	ds_read_b128 v[182:185], v149 offset:33792
	ds_read_b128 v[186:189], v149 offset:34816
	ds_read_b128 v[190:193], v149 offset:35840
	ds_read_b128 v[202:205], v149 offset:36864
	ds_read_b128 v[206:209], v149 offset:37888
	ds_read_b128 v[210:213], v149 offset:38912
	ds_read_b128 v[214:217], v149 offset:39936
	global_load_lds_dwordx4 v[222:223], off
	v_lshl_add_u64 v[222:223], s[40:41], 0, v[132:133]
	s_mov_b32 m0, s47
	s_nop 0
	global_load_lds_dwordx4 v[222:223], off
	s_waitcnt vmcnt(8)
	s_waitcnt lgkmcnt(0)
	v_mfma_f32_16x16x32_bf16 v[128:131], v[140:143], v[178:181], v[128:131]
	v_mfma_f32_16x16x32_bf16 v[124:127], v[154:157], v[178:181], v[124:127]
	v_mfma_f32_16x16x32_bf16 v[112:115], v[140:143], v[186:189], v[112:115]
	v_mfma_f32_16x16x32_bf16 v[108:111], v[154:157], v[186:189], v[108:111]
	v_mfma_f32_16x16x32_bf16 v[96:99], v[140:143], v[202:205], v[96:99]
	v_mfma_f32_16x16x32_bf16 v[92:95], v[154:157], v[202:205], v[92:95]
	v_mfma_f32_16x16x32_bf16 v[80:83], v[140:143], v[210:213], v[80:83]
	v_mfma_f32_16x16x32_bf16 v[76:79], v[154:157], v[210:213], v[76:79]
	s_barrier
	s_setprio 1
	v_mfma_f32_16x16x32_bf16 v[128:131], v[150:153], v[182:185], v[128:131]
	v_mfma_f32_16x16x32_bf16 v[124:127], v[158:161], v[182:185], v[124:127]
	v_mfma_f32_16x16x32_bf16 v[112:115], v[150:153], v[190:193], v[112:115]
	v_mfma_f32_16x16x32_bf16 v[108:111], v[158:161], v[190:193], v[108:111]
	v_mfma_f32_16x16x32_bf16 v[96:99], v[150:153], v[206:209], v[96:99]
	v_mfma_f32_16x16x32_bf16 v[92:95], v[158:161], v[206:209], v[92:95]
	v_mfma_f32_16x16x32_bf16 v[80:83], v[150:153], v[214:217], v[80:83]
	v_mfma_f32_16x16x32_bf16 v[76:79], v[158:161], v[214:217], v[76:79]
	s_setprio 0
	s_setprio 1
	v_mfma_f32_16x16x32_bf16 v[120:123], v[162:165], v[178:181], v[120:123]
	v_mfma_f32_16x16x32_bf16 v[116:119], v[170:173], v[178:181], v[116:119]
	v_mfma_f32_16x16x32_bf16 v[104:107], v[162:165], v[186:189], v[104:107]
	v_mfma_f32_16x16x32_bf16 v[100:103], v[170:173], v[186:189], v[100:103]
	v_mfma_f32_16x16x32_bf16 v[88:91], v[162:165], v[202:205], v[88:91]
	v_mfma_f32_16x16x32_bf16 v[84:87], v[170:173], v[202:205], v[84:87]
	v_mfma_f32_16x16x32_bf16 v[72:75], v[162:165], v[210:213], v[72:75]
	v_mfma_f32_16x16x32_bf16 v[68:71], v[170:173], v[210:213], v[68:71]
	v_mfma_f32_16x16x32_bf16 v[120:123], v[166:169], v[182:185], v[120:123]
	v_mfma_f32_16x16x32_bf16 v[116:119], v[174:177], v[182:185], v[116:119]
	v_mfma_f32_16x16x32_bf16 v[104:107], v[166:169], v[190:193], v[104:107]
	v_mfma_f32_16x16x32_bf16 v[100:103], v[174:177], v[190:193], v[100:103]
	v_mfma_f32_16x16x32_bf16 v[88:91], v[166:169], v[206:209], v[88:91]
	v_mfma_f32_16x16x32_bf16 v[84:87], v[174:177], v[206:209], v[84:87]
	v_mfma_f32_16x16x32_bf16 v[72:75], v[166:169], v[214:217], v[72:75]
	v_mfma_f32_16x16x32_bf16 v[68:71], v[174:177], v[214:217], v[68:71]
	s_setprio 0
	s_barrier
; #define PG8_STAGE(bufoff, gbase, voff) do { _Pragma("unroll") for (int _i = 0; _i < 2; ++_i) \
;         __builtin_amdgcn_global_load_lds((const unsigned*)((const char*)(gbase) + (voff)[_i]), (PG8_LAS unsigned*)(lds + (bufoff) + ldsw + _i * 8192), 16, 0, 0); } while (0)
; #define PG8_LDA(dst, b, h) do { _Pragma("unroll") for (int m = 0; m < 4; ++m) _Pragma("unroll") for (int k = 0; k < 2; ++k) dst[m][k] = *(const PG8_LAS bf16x8*)(lds + PG8_SA(b, h) + aoff + m * 2048 + k * 1024); } while (0)
; #define PG8_MMA(ai, bj, At, Bt) do { __builtin_amdgcn_s_setprio(1); _Pragma("unroll") for (int m = 0; m < 4; ++m) _Pragma("unroll") for (int n = 0; n < 2; ++n) _Pragma("unroll") for (int k = 0; k < 2; ++k) \
;         acc[ai][bj][m][n] = __builtin_amdgcn_mfma_f32_16x16x32_bf16(Bt[n][k], At[m][k], acc[ai][bj][m][n], 0, 0, 0); __builtin_amdgcn_s_setprio(0); } while (0)
; #define PG8_WAIT_V(n) asm volatile("s_waitcnt vmcnt(" #n ")" ::: "memory")
; #define PG8_WAIT_L(n) asm volatile("s_waitcnt lgkmcnt(" #n ")" ::: "memory")
; #define PG8_BAR __builtin_amdgcn_s_barrier()
; #define PG8_SCHED __builtin_amdgcn_sched_barrier(0)
; template <class Epi, class Sched, bool ALIGN_EPI = false, bool SP2 = false>
; __device__ __forceinline__ void gemm_phase(PG8_LAS unsigned char* lds, const Gemm g, const Sched& S, const Epi& E) {
;     ...
;         for (int t = 0; t < nt; t += 2) {
;     ...
;             PG8_LDA(At, 1, 1); PG8_STAGE(PG8_SB(1, 0), b3, voffB); PG8_STAGE(PG8_SB(1, 1), b3 + hstep, voffB); PG8_STAGE(PG8_SA(1, 0), a3, voffA);
;             PG8_WAIT_V(8); PG8_WAIT_L(0); PG8_BAR; PG8_MMA(1, 0, At, B0); PG8_MMA(1, 1, At, B1); PG8_BAR; PG8_SCHED;
	s_add_i32 s40, s58, s43
	v_lshl_add_u64 v[144:145], v[144:145], 0, s[36:37]
	s_mov_b32 m0, s40
	ds_read_b128 v[178:181], v149 offset:49152
	ds_read_b128 v[182:185], v149 offset:50176
	ds_read_b128 v[186:189], v149 offset:51200
	ds_read_b128 v[190:193], v149 offset:52224
	ds_read_b128 v[202:205], v149 offset:53248
	ds_read_b128 v[206:209], v149 offset:54272
	ds_read_b128 v[210:213], v149 offset:55296
	ds_read_b128 v[214:217], v149 offset:56320
	global_load_lds_dwordx4 v[144:145], off
	s_add_i32 m0, s40, 0x2000
	s_add_u32 s22, s22, 0x40080
	v_lshl_add_u64 v[144:145], v[194:195], 0, s[36:37]
	s_addc_u32 s23, s23, 0
	s_add_i32 s40, s59, s43
	global_load_lds_dwordx4 v[144:145], off
	v_lshl_add_u64 v[144:145], s[22:23], 0, v[196:197]
	s_mov_b32 m0, s40
	s_nop 0
	global_load_lds_dwordx4 v[144:145], off
	v_lshl_add_u64 v[144:145], s[22:23], 0, v[32:33]
	s_add_i32 m0, s40, 0x2000
	s_nop 0
	global_load_lds_dwordx4 v[144:145], off
	v_lshl_add_u64 v[144:145], v[218:219], 0, s[36:37]
	s_mov_b32 m0, s49
	s_nop 0
	global_load_lds_dwordx4 v[144:145], off
	v_lshl_add_u64 v[144:145], v[220:221], 0, s[36:37]
	s_mov_b32 m0, s50
	s_nop 0
	global_load_lds_dwordx4 v[144:145], off
	s_waitcnt vmcnt(8)
	s_waitcnt lgkmcnt(0)
	v_mfma_f32_16x16x32_bf16 v[64:67], v[140:143], v[178:181], v[64:67]
	v_mfma_f32_16x16x32_bf16 v[60:63], v[154:157], v[178:181], v[60:63]
	v_mfma_f32_16x16x32_bf16 v[48:51], v[140:143], v[186:189], v[48:51]
	v_mfma_f32_16x16x32_bf16 v[44:47], v[154:157], v[186:189], v[44:47]
	v_mfma_f32_16x16x32_bf16 v[28:31], v[140:143], v[202:205], v[28:31]
	v_mfma_f32_16x16x32_bf16 v[24:27], v[154:157], v[202:205], v[24:27]
	v_mfma_f32_16x16x32_bf16 v[12:15], v[140:143], v[210:213], v[12:15]
	v_mfma_f32_16x16x32_bf16 v[8:11], v[154:157], v[210:213], v[8:11]
	s_barrier
	s_setprio 1
	v_mfma_f32_16x16x32_bf16 v[64:67], v[150:153], v[182:185], v[64:67]
	v_mfma_f32_16x16x32_bf16 v[60:63], v[158:161], v[182:185], v[60:63]
	v_mfma_f32_16x16x32_bf16 v[48:51], v[150:153], v[190:193], v[48:51]
	v_mfma_f32_16x16x32_bf16 v[44:47], v[158:161], v[190:193], v[44:47]
	v_mfma_f32_16x16x32_bf16 v[28:31], v[150:153], v[206:209], v[28:31]
	v_mfma_f32_16x16x32_bf16 v[24:27], v[158:161], v[206:209], v[24:27]
	v_mfma_f32_16x16x32_bf16 v[12:15], v[150:153], v[214:217], v[12:15]
	v_mfma_f32_16x16x32_bf16 v[8:11], v[158:161], v[214:217], v[8:11]
	s_setprio 0
	s_setprio 1
	v_mfma_f32_16x16x32_bf16 v[56:59], v[162:165], v[178:181], v[56:59]
	v_mfma_f32_16x16x32_bf16 v[52:55], v[170:173], v[178:181], v[52:55]
	v_mfma_f32_16x16x32_bf16 v[40:43], v[162:165], v[186:189], v[40:43]
	v_mfma_f32_16x16x32_bf16 v[36:39], v[170:173], v[186:189], v[36:39]
	v_mfma_f32_16x16x32_bf16 v[20:23], v[162:165], v[202:205], v[20:23]
	v_mfma_f32_16x16x32_bf16 v[16:19], v[170:173], v[202:205], v[16:19]
	v_mfma_f32_16x16x32_bf16 v[4:7], v[162:165], v[210:213], v[4:7]
	v_mfma_f32_16x16x32_bf16 v[0:3], v[170:173], v[210:213], v[0:3]
	v_mfma_f32_16x16x32_bf16 v[56:59], v[166:169], v[182:185], v[56:59]
	v_mfma_f32_16x16x32_bf16 v[52:55], v[174:177], v[182:185], v[52:55]
	v_mfma_f32_16x16x32_bf16 v[40:43], v[166:169], v[190:193], v[40:43]
	v_mfma_f32_16x16x32_bf16 v[36:39], v[174:177], v[190:193], v[36:39]
	v_mfma_f32_16x16x32_bf16 v[20:23], v[166:169], v[206:209], v[20:23]
	v_mfma_f32_16x16x32_bf16 v[16:19], v[174:177], v[206:209], v[16:19]
	v_mfma_f32_16x16x32_bf16 v[4:7], v[166:169], v[214:217], v[4:7]
	v_mfma_f32_16x16x32_bf16 v[0:3], v[174:177], v[214:217], v[0:3]
	s_setprio 0
	s_barrier
	s_add_i32 s57, s57, 2
	s_add_u32 s0, s0, 0x100
	s_addc_u32 s1, s1, 0
	s_add_u32 s55, s55, 0x100
	s_addc_u32 s56, s56, 0
	s_cmp_gt_u32 s57, 13
	s_cbranch_scc0 .LBB0_623
	s_and_b64 vcc, exec, s[12:13]
	s_cbranch_vccz .LBB0_626
	s_barrier
